# third gated-merge GEMM epilogue: gate and accumulator tiles prefetched 4 pieces at a time (was load-wait per piece)
# speedup vs baseline: 1.1314x; 1.0042x over previous
; #define PG8_STAGE(bufoff, gbase, voff) do { _Pragma("unroll") for (int _i = 0; _i < 2; ++_i) \
;         __builtin_amdgcn_global_load_lds((const unsigned*)((const char*)(gbase) + (voff)[_i]), (PG8_LAS unsigned*)(lds + (bufoff) + ldsw + _i * 8192), 16, 0, 0); } while (0)
; #define PG8_LDA(dst, b, h) do { _Pragma("unroll") for (int m = 0; m < 4; ++m) _Pragma("unroll") for (int k = 0; k < 2; ++k) dst[m][k] = *(const PG8_LAS bf16x8*)(lds + PG8_SA(b, h) + aoff + m * 2048 + k * 1024); } while (0)
; #define PG8_LDB(dst, b, h) do { _Pragma("unroll") for (int n = 0; n < 2; ++n) _Pragma("unroll") for (int k = 0; k < 2; ++k) dst[n][k] = *(const PG8_LAS bf16x8*)(lds + PG8_SB(b, h) + boff + n * 2048 + k * 1024); } while (0)
; #define PG8_MMA(ai, bj, At, Bt) do { __builtin_amdgcn_s_setprio(1); _Pragma("unroll") for (int m = 0; m < 4; ++m) _Pragma("unroll") for (int n = 0; n < 2; ++n) _Pragma("unroll") for (int k = 0; k < 2; ++k) \
;         acc[ai][bj][m][n] = __builtin_amdgcn_mfma_f32_16x16x32_bf16(Bt[n][k], At[m][k], acc[ai][bj][m][n], 0, 0, 0); __builtin_amdgcn_s_setprio(0); } while (0)
; #define PG8_WAIT_V(n) asm volatile("s_waitcnt vmcnt(" #n ")" ::: "memory")
; #define PG8_WAIT_L(n) asm volatile("s_waitcnt lgkmcnt(" #n ")" ::: "memory")
; #define PG8_BAR __builtin_amdgcn_s_barrier()
; #define PG8_SCHED __builtin_amdgcn_sched_barrier(0)
; template <class Epi, class Sched>
; __device__ __forceinline__ void gemm_phase(PG8_LAS unsigned char* lds, const Gemm g, const Sched& S, const Epi& E, const int tid_in) {
;     ...
;             PG8_LDB(B0, 0, 0); PG8_SCHED; PG8_LDA(At, 0, 0); PG8_STAGE(PG8_SA(1, 1), a1 + hstepA, voffA);
;             PG8_WAIT_L(8); PG8_BAR; PG8_WAIT_L(0); PG8_MMA(0, 0, At, B0); PG8_BAR; PG8_SCHED;
;             PG8_LDB(B1, 0, 1); PG8_STAGE(PG8_SB(0, 0), b2, voffB);
;             PG8_BAR; PG8_WAIT_L(0); PG8_MMA(0, 1, At, B1); PG8_BAR;
;             PG8_LDA(At, 0, 1); PG8_STAGE(PG8_SA(0, 0), a2, voffA);
;             PG8_BAR; PG8_WAIT_L(0); PG8_MMA(1, 0, At, B0); PG8_BAR; PG8_SCHED;
;             PG8_STAGE(PG8_SB(0, 1), b2 + hstepB, voffB);
;             PG8_WAIT_V(6); PG8_BAR; PG8_MMA(1, 1, At, B1); PG8_BAR;
.LBB0_1863:
	v_add_u32_e32 v136, s34, v157
	ds_read_b128 v[148:151], v136
	ds_read_b128 v[152:155], v136 offset:1024
	ds_read_b128 v[184:187], v136 offset:2048
	ds_read_b128 v[188:191], v136 offset:3072
	s_add_u32 s4, s16, 0x100
	s_addc_u32 s5, s17, 0
	s_cmp_eq_u32 s59, 12
	s_cselect_b32 s21, s13, s5
	s_cselect_b32 s20, s12, s4
	s_cselect_b32 s19, s11, s58
	s_cselect_b32 s18, s56, s57
	v_lshl_add_u64 v[136:137], s[16:17], 0, v[144:145]
	s_add_i32 m0, s37, 0xc000
	ds_read_b128 v[192:195], v159
	ds_read_b128 v[196:199], v159 offset:1024
	ds_read_b128 v[200:203], v159 offset:2048
	ds_read_b128 v[204:207], v159 offset:3072
	ds_read_b128 v[208:211], v159 offset:4096
	ds_read_b128 v[212:215], v159 offset:5120
	ds_read_b128 v[216:219], v159 offset:6144
	ds_read_b128 v[220:223], v159 offset:7168
	global_load_lds_dwordx4 v[136:137], off
	v_lshl_add_u64 v[136:137], s[16:17], 0, v[146:147]
	s_add_i32 m0, s37, 0xe000
	s_nop 0
	global_load_lds_dwordx4 v[136:137], off
	s_waitcnt lgkmcnt(8)
	s_barrier
	s_waitcnt lgkmcnt(0)
	s_setprio 1
	s_waitcnt lgkmcnt(0)
	v_mfma_f32_16x16x32_bf16 v[128:131], v[148:151], v[192:195], v[128:131]
	v_mfma_f32_16x16x32_bf16 v[124:127], v[184:187], v[192:195], v[124:127]
	v_mfma_f32_16x16x32_bf16 v[112:115], v[148:151], v[200:203], v[112:115]
	v_mfma_f32_16x16x32_bf16 v[108:111], v[184:187], v[200:203], v[108:111]
	v_mfma_f32_16x16x32_bf16 v[96:99], v[148:151], v[208:211], v[96:99]
	v_mfma_f32_16x16x32_bf16 v[92:95], v[184:187], v[208:211], v[92:95]
	v_mfma_f32_16x16x32_bf16 v[80:83], v[148:151], v[216:219], v[80:83]
	v_mfma_f32_16x16x32_bf16 v[76:79], v[184:187], v[216:219], v[76:79]
	v_mfma_f32_16x16x32_bf16 v[128:131], v[152:155], v[196:199], v[128:131]
	v_mfma_f32_16x16x32_bf16 v[124:127], v[188:191], v[196:199], v[124:127]
	v_mfma_f32_16x16x32_bf16 v[112:115], v[152:155], v[204:207], v[112:115]
	v_mfma_f32_16x16x32_bf16 v[108:111], v[188:191], v[204:207], v[108:111]
	v_mfma_f32_16x16x32_bf16 v[96:99], v[152:155], v[212:215], v[96:99]
	v_mfma_f32_16x16x32_bf16 v[92:95], v[188:191], v[212:215], v[92:95]
	v_mfma_f32_16x16x32_bf16 v[80:83], v[152:155], v[220:223], v[80:83]
	v_mfma_f32_16x16x32_bf16 v[76:79], v[188:191], v[220:223], v[76:79]
	s_setprio 0
	s_barrier
	v_add_u32_e32 v136, s39, v157
	s_mov_b32 m0, s35
	ds_read_b128 v[224:227], v136
	ds_read_b128 v[228:231], v136 offset:1024
	ds_read_b128 v[232:235], v136 offset:2048
	ds_read_b128 v[236:239], v136 offset:3072
	v_lshl_add_u64 v[136:137], s[18:19], 0, v[30:31]
	global_load_lds_dwordx4 v[136:137], off
	v_lshl_add_u64 v[138:139], s[18:19], 0, v[134:135]
	s_mov_b32 m0, s36
	s_nop 0
	global_load_lds_dwordx4 v[138:139], off
	s_barrier
	s_waitcnt lgkmcnt(0)
	s_setprio 1
	s_waitcnt lgkmcnt(0)
	v_mfma_f32_16x16x32_bf16 v[120:123], v[224:227], v[192:195], v[120:123]
	v_mfma_f32_16x16x32_bf16 v[116:119], v[232:235], v[192:195], v[116:119]
	v_mfma_f32_16x16x32_bf16 v[104:107], v[224:227], v[200:203], v[104:107]
	v_mfma_f32_16x16x32_bf16 v[100:103], v[232:235], v[200:203], v[100:103]
	v_mfma_f32_16x16x32_bf16 v[88:91], v[224:227], v[208:211], v[88:91]
	v_mfma_f32_16x16x32_bf16 v[84:87], v[232:235], v[208:211], v[84:87]
	v_mfma_f32_16x16x32_bf16 v[72:75], v[224:227], v[216:219], v[72:75]
	v_mfma_f32_16x16x32_bf16 v[68:71], v[232:235], v[216:219], v[68:71]
	v_mfma_f32_16x16x32_bf16 v[120:123], v[228:231], v[196:199], v[120:123]
	v_mfma_f32_16x16x32_bf16 v[116:119], v[236:239], v[196:199], v[116:119]
	v_mfma_f32_16x16x32_bf16 v[104:107], v[228:231], v[204:207], v[104:107]
	v_mfma_f32_16x16x32_bf16 v[100:103], v[236:239], v[204:207], v[100:103]
	v_mfma_f32_16x16x32_bf16 v[88:91], v[228:231], v[212:215], v[88:91]
	v_mfma_f32_16x16x32_bf16 v[84:87], v[236:239], v[212:215], v[84:87]
	v_mfma_f32_16x16x32_bf16 v[72:75], v[228:231], v[220:223], v[72:75]
	v_mfma_f32_16x16x32_bf16 v[68:71], v[236:239], v[220:223], v[68:71]
	s_setprio 0
	s_mov_b32 m0, s37
	v_lshl_add_u64 v[160:161], s[20:21], 0, v[28:29]
	s_barrier
	ds_read_b128 v[192:195], v159 offset:16384
	ds_read_b128 v[196:199], v159 offset:17408
	ds_read_b128 v[200:203], v159 offset:18432
	ds_read_b128 v[204:207], v159 offset:19456
	ds_read_b128 v[208:211], v159 offset:20480
	ds_read_b128 v[212:215], v159 offset:21504
	ds_read_b128 v[216:219], v159 offset:22528
	ds_read_b128 v[220:223], v159 offset:23552
	global_load_lds_dwordx4 v[160:161], off
	v_lshl_add_u64 v[240:241], s[20:21], 0, v[132:133]
	s_mov_b32 m0, s38
	s_nop 0
	global_load_lds_dwordx4 v[240:241], off
	s_barrier
	s_waitcnt lgkmcnt(0)
	s_setprio 1
	s_waitcnt lgkmcnt(0)
	v_mfma_f32_16x16x32_bf16 v[64:67], v[148:151], v[192:195], v[64:67]
	v_mfma_f32_16x16x32_bf16 v[60:63], v[184:187], v[192:195], v[60:63]
	v_mfma_f32_16x16x32_bf16 v[48:51], v[148:151], v[200:203], v[48:51]
	v_mfma_f32_16x16x32_bf16 v[44:47], v[184:187], v[200:203], v[44:47]
	v_mfma_f32_16x16x32_bf16 v[32:35], v[148:151], v[208:211], v[32:35]
	v_mfma_f32_16x16x32_bf16 v[24:27], v[184:187], v[208:211], v[24:27]
	v_mfma_f32_16x16x32_bf16 v[12:15], v[148:151], v[216:219], v[12:15]
	v_mfma_f32_16x16x32_bf16 v[8:11], v[184:187], v[216:219], v[8:11]
	v_mfma_f32_16x16x32_bf16 v[64:67], v[152:155], v[196:199], v[64:67]
	v_mfma_f32_16x16x32_bf16 v[60:63], v[188:191], v[196:199], v[60:63]
	v_mfma_f32_16x16x32_bf16 v[48:51], v[152:155], v[204:207], v[48:51]
	v_mfma_f32_16x16x32_bf16 v[44:47], v[188:191], v[204:207], v[44:47]
	v_mfma_f32_16x16x32_bf16 v[32:35], v[152:155], v[212:215], v[32:35]
	v_mfma_f32_16x16x32_bf16 v[24:27], v[188:191], v[212:215], v[24:27]
	v_mfma_f32_16x16x32_bf16 v[12:15], v[152:155], v[220:223], v[12:15]
	v_mfma_f32_16x16x32_bf16 v[8:11], v[188:191], v[220:223], v[8:11]
	s_setprio 0
	s_barrier
; #define PG8_STAGE(bufoff, gbase, voff) do { _Pragma("unroll") for (int _i = 0; _i < 2; ++_i) \
;         __builtin_amdgcn_global_load_lds((const unsigned*)((const char*)(gbase) + (voff)[_i]), (PG8_LAS unsigned*)(lds + (bufoff) + ldsw + _i * 8192), 16, 0, 0); } while (0)
; #define PG8_LDA(dst, b, h) do { _Pragma("unroll") for (int m = 0; m < 4; ++m) _Pragma("unroll") for (int k = 0; k < 2; ++k) dst[m][k] = *(const PG8_LAS bf16x8*)(lds + PG8_SA(b, h) + aoff + m * 2048 + k * 1024); } while (0)
; #define PG8_LDB(dst, b, h) do { _Pragma("unroll") for (int n = 0; n < 2; ++n) _Pragma("unroll") for (int k = 0; k < 2; ++k) dst[n][k] = *(const PG8_LAS bf16x8*)(lds + PG8_SB(b, h) + boff + n * 2048 + k * 1024); } while (0)
; #define PG8_MMA(ai, bj, At, Bt) do { __builtin_amdgcn_s_setprio(1); _Pragma("unroll") for (int m = 0; m < 4; ++m) _Pragma("unroll") for (int n = 0; n < 2; ++n) _Pragma("unroll") for (int k = 0; k < 2; ++k) \
;         acc[ai][bj][m][n] = __builtin_amdgcn_mfma_f32_16x16x32_bf16(Bt[n][k], At[m][k], acc[ai][bj][m][n], 0, 0, 0); __builtin_amdgcn_s_setprio(0); } while (0)
; #define PG8_WAIT_V(n) asm volatile("s_waitcnt vmcnt(" #n ")" ::: "memory")
; #define PG8_WAIT_L(n) asm volatile("s_waitcnt lgkmcnt(" #n ")" ::: "memory")
; #define PG8_BAR __builtin_amdgcn_s_barrier()
; #define PG8_SCHED __builtin_amdgcn_sched_barrier(0)
; template <class Epi, class Sched>
; __device__ __forceinline__ void gemm_phase(PG8_LAS unsigned char* lds, const Gemm g, const Sched& S, const Epi& E, const int tid_in) {
;     ...
;             PG8_STAGE(PG8_SB(0, 1), b2 + hstepB, voffB);
;             PG8_WAIT_V(6); PG8_BAR; PG8_MMA(1, 1, At, B1); PG8_BAR;
;             PG8_LDB(B0, 1, 0); PG8_SCHED; PG8_LDA(At, 1, 0); PG8_STAGE(PG8_SA(0, 1), a2 + hstepA, voffA);
;             PG8_WAIT_L(8); PG8_BAR; PG8_WAIT_L(0); PG8_MMA(0, 0, At, B0); PG8_BAR; PG8_SCHED;
;             PG8_LDB(B1, 1, 1); PG8_STAGE(PG8_SB(1, 0), b3, voffB);
;             PG8_BAR; PG8_WAIT_L(0); PG8_MMA(0, 1, At, B1); PG8_BAR;
;             PG8_LDA(At, 1, 1); PG8_STAGE(PG8_SA(1, 0), a3, voffA);
;             PG8_BAR; PG8_WAIT_L(0); PG8_MMA(1, 0, At, B0); PG8_BAR; PG8_SCHED;
	s_add_u32 s16, s18, 0x40000
	s_addc_u32 s17, s19, 0
	s_mov_b32 m0, s40
	v_lshl_add_u64 v[148:149], s[16:17], 0, v[30:31]
	global_load_lds_dwordx4 v[148:149], off
	v_lshl_add_u64 v[148:149], s[16:17], 0, v[134:135]
	s_mov_b32 m0, s41
	s_nop 0
	global_load_lds_dwordx4 v[148:149], off
	s_waitcnt vmcnt(6)
	s_barrier
	s_setprio 1
	v_mfma_f32_16x16x32_bf16 v[56:59], v[224:227], v[192:195], v[56:59]
	v_mfma_f32_16x16x32_bf16 v[52:55], v[232:235], v[192:195], v[52:55]
	v_mfma_f32_16x16x32_bf16 v[40:43], v[224:227], v[200:203], v[40:43]
	v_mfma_f32_16x16x32_bf16 v[36:39], v[232:235], v[200:203], v[36:39]
	v_mfma_f32_16x16x32_bf16 v[20:23], v[224:227], v[208:211], v[20:23]
	v_mfma_f32_16x16x32_bf16 v[16:19], v[232:235], v[208:211], v[16:19]
	v_mfma_f32_16x16x32_bf16 v[4:7], v[224:227], v[216:219], v[4:7]
	v_mfma_f32_16x16x32_bf16 v[0:3], v[232:235], v[216:219], v[0:3]
	v_mfma_f32_16x16x32_bf16 v[56:59], v[228:231], v[196:199], v[56:59]
	v_mfma_f32_16x16x32_bf16 v[52:55], v[236:239], v[196:199], v[52:55]
	v_mfma_f32_16x16x32_bf16 v[40:43], v[228:231], v[204:207], v[40:43]
	v_mfma_f32_16x16x32_bf16 v[36:39], v[236:239], v[204:207], v[36:39]
	v_mfma_f32_16x16x32_bf16 v[20:23], v[228:231], v[212:215], v[20:23]
	v_mfma_f32_16x16x32_bf16 v[16:19], v[236:239], v[212:215], v[16:19]
	v_mfma_f32_16x16x32_bf16 v[4:7], v[228:231], v[220:223], v[4:7]
	v_mfma_f32_16x16x32_bf16 v[0:3], v[236:239], v[220:223], v[0:3]
	s_setprio 0
	v_add_u32_e32 v188, s44, v157
	s_barrier
	ds_read_b128 v[148:151], v188
	ds_read_b128 v[152:155], v188 offset:1024
	ds_read_b128 v[184:187], v188 offset:2048
	ds_read_b128 v[188:191], v188 offset:3072
	s_add_u32 s16, s20, 0x210000
	s_addc_u32 s17, s21, 0
	s_mov_b32 m0, s42
	v_lshl_add_u64 v[224:225], s[16:17], 0, v[28:29]
	ds_read_b128 v[192:195], v159 offset:32768
	ds_read_b128 v[196:199], v159 offset:33792
	ds_read_b128 v[200:203], v159 offset:34816
	ds_read_b128 v[204:207], v159 offset:35840
	ds_read_b128 v[208:211], v159 offset:36864
	ds_read_b128 v[212:215], v159 offset:37888
	ds_read_b128 v[216:219], v159 offset:38912
	ds_read_b128 v[220:223], v159 offset:39936
	global_load_lds_dwordx4 v[224:225], off
	v_lshl_add_u64 v[224:225], s[16:17], 0, v[132:133]
	s_mov_b32 m0, s43
	s_nop 0
	global_load_lds_dwordx4 v[224:225], off
	s_waitcnt lgkmcnt(8)
	s_barrier
	s_waitcnt lgkmcnt(0)
	s_setprio 1
	s_waitcnt lgkmcnt(0)
	v_mfma_f32_16x16x32_bf16 v[128:131], v[148:151], v[192:195], v[128:131]
	v_mfma_f32_16x16x32_bf16 v[124:127], v[184:187], v[192:195], v[124:127]
	v_mfma_f32_16x16x32_bf16 v[112:115], v[148:151], v[200:203], v[112:115]
	v_mfma_f32_16x16x32_bf16 v[108:111], v[184:187], v[200:203], v[108:111]
	v_mfma_f32_16x16x32_bf16 v[96:99], v[148:151], v[208:211], v[96:99]
	v_mfma_f32_16x16x32_bf16 v[92:95], v[184:187], v[208:211], v[92:95]
	v_mfma_f32_16x16x32_bf16 v[80:83], v[148:151], v[216:219], v[80:83]
	v_mfma_f32_16x16x32_bf16 v[76:79], v[184:187], v[216:219], v[76:79]
	v_mfma_f32_16x16x32_bf16 v[128:131], v[152:155], v[196:199], v[128:131]
	v_mfma_f32_16x16x32_bf16 v[124:127], v[188:191], v[196:199], v[124:127]
	v_mfma_f32_16x16x32_bf16 v[112:115], v[152:155], v[204:207], v[112:115]
	v_mfma_f32_16x16x32_bf16 v[108:111], v[188:191], v[204:207], v[108:111]
	v_mfma_f32_16x16x32_bf16 v[96:99], v[152:155], v[212:215], v[96:99]
	v_mfma_f32_16x16x32_bf16 v[92:95], v[188:191], v[212:215], v[92:95]
	v_mfma_f32_16x16x32_bf16 v[80:83], v[152:155], v[220:223], v[80:83]
	v_mfma_f32_16x16x32_bf16 v[76:79], v[188:191], v[220:223], v[76:79]
	s_setprio 0
	s_barrier
	s_mov_b32 m0, s45
	v_add_u32_e32 v236, s49, v157
	v_lshl_add_u64 v[136:137], v[136:137], 0, s[94:95]
	ds_read_b128 v[224:227], v236
	ds_read_b128 v[228:231], v236 offset:1024
	ds_read_b128 v[232:235], v236 offset:2048
	ds_read_b128 v[236:239], v236 offset:3072
	global_load_lds_dwordx4 v[136:137], off
	v_lshl_add_u64 v[136:137], v[138:139], 0, s[94:95]
	s_mov_b32 m0, s46
	s_nop 0
	global_load_lds_dwordx4 v[136:137], off
	s_barrier
	s_waitcnt lgkmcnt(0)
	s_setprio 1
	s_waitcnt lgkmcnt(0)
	v_mfma_f32_16x16x32_bf16 v[120:123], v[224:227], v[192:195], v[120:123]
	v_mfma_f32_16x16x32_bf16 v[116:119], v[232:235], v[192:195], v[116:119]
	v_mfma_f32_16x16x32_bf16 v[104:107], v[224:227], v[200:203], v[104:107]
	v_mfma_f32_16x16x32_bf16 v[100:103], v[232:235], v[200:203], v[100:103]
	v_mfma_f32_16x16x32_bf16 v[88:91], v[224:227], v[208:211], v[88:91]
	v_mfma_f32_16x16x32_bf16 v[84:87], v[232:235], v[208:211], v[84:87]
	v_mfma_f32_16x16x32_bf16 v[72:75], v[224:227], v[216:219], v[72:75]
	v_mfma_f32_16x16x32_bf16 v[68:71], v[232:235], v[216:219], v[68:71]
	v_mfma_f32_16x16x32_bf16 v[120:123], v[228:231], v[196:199], v[120:123]
	v_mfma_f32_16x16x32_bf16 v[116:119], v[236:239], v[196:199], v[116:119]
	v_mfma_f32_16x16x32_bf16 v[104:107], v[228:231], v[204:207], v[104:107]
	v_mfma_f32_16x16x32_bf16 v[100:103], v[236:239], v[204:207], v[100:103]
	v_mfma_f32_16x16x32_bf16 v[88:91], v[228:231], v[212:215], v[88:91]
	v_mfma_f32_16x16x32_bf16 v[84:87], v[236:239], v[212:215], v[84:87]
	v_mfma_f32_16x16x32_bf16 v[72:75], v[228:231], v[220:223], v[72:75]
	v_mfma_f32_16x16x32_bf16 v[68:71], v[236:239], v[220:223], v[68:71]
	s_setprio 0
	s_mov_b32 m0, s47
	v_lshl_add_u64 v[136:137], v[160:161], 0, s[94:95]
	s_barrier
	ds_read_b128 v[192:195], v159 offset:49152
	ds_read_b128 v[196:199], v159 offset:50176
	ds_read_b128 v[200:203], v159 offset:51200
	ds_read_b128 v[204:207], v159 offset:52224
	ds_read_b128 v[208:211], v159 offset:53248
	ds_read_b128 v[212:215], v159 offset:54272
	ds_read_b128 v[216:219], v159 offset:55296
	ds_read_b128 v[220:223], v159 offset:56320
	global_load_lds_dwordx4 v[136:137], off
	v_lshl_add_u64 v[136:137], v[240:241], 0, s[94:95]
	s_mov_b32 m0, s48
	s_nop 0
	global_load_lds_dwordx4 v[136:137], off
	s_barrier
; #define PG8_STAGE(bufoff, gbase, voff) do { _Pragma("unroll") for (int _i = 0; _i < 2; ++_i) \
;         __builtin_amdgcn_global_load_lds((const unsigned*)((const char*)(gbase) + (voff)[_i]), (PG8_LAS unsigned*)(lds + (bufoff) + ldsw + _i * 8192), 16, 0, 0); } while (0)
; #define PG8_MMA(ai, bj, At, Bt) do { __builtin_amdgcn_s_setprio(1); _Pragma("unroll") for (int m = 0; m < 4; ++m) _Pragma("unroll") for (int n = 0; n < 2; ++n) _Pragma("unroll") for (int k = 0; k < 2; ++k) \
;         acc[ai][bj][m][n] = __builtin_amdgcn_mfma_f32_16x16x32_bf16(Bt[n][k], At[m][k], acc[ai][bj][m][n], 0, 0, 0); __builtin_amdgcn_s_setprio(0); } while (0)
; #define PG8_WAIT_V(n) asm volatile("s_waitcnt vmcnt(" #n ")" ::: "memory")
; #define PG8_WAIT_L(n) asm volatile("s_waitcnt lgkmcnt(" #n ")" ::: "memory")
; #define PG8_BAR __builtin_amdgcn_s_barrier()
; #define PG8_SCHED __builtin_amdgcn_sched_barrier(0)
; template <class Epi, class Sched>
; __device__ __forceinline__ void gemm_phase(PG8_LAS unsigned char* lds, const Gemm g, const Sched& S, const Epi& E, const int tid_in) {
;     ...
;             PG8_BAR; PG8_WAIT_L(0); PG8_MMA(1, 0, At, B0); PG8_BAR; PG8_SCHED;
;             PG8_STAGE(PG8_SB(1, 1), b3 + hstepB, voffB);
;             PG8_WAIT_V(6); PG8_BAR; PG8_MMA(1, 1, At, B1); PG8_BAR;
;     __device__ __forceinline__ void operator()(const f32x4 (&acc)[2][2][4][2], const pg8::Unit& u, int wr, int wc, int fr, int fq) const {
;         const int row0 = u.pm * 256 + wr * 64 + fr, col0 = u.pn * 256 + wc * 32 + 8 * fq;
; #pragma unroll
;         for (int ai = 0; ai < 2; ++ai)
; #pragma unroll
;             for (int m = 0; m < 4; ++m) {
;                 const size_t row = (size_t)(row0 + ai * 128 + m * 16);
; #pragma unroll
;                 for (int bj = 0; bj < 2; ++bj) {
;                     float gt[8], mv[8], o[8];
;                     unpack8(*(const u32x4*)(Z + row * ZW + goff + col0 + bj * 128), gt);
;                     if (!first) unpack8(*(const u32x4*)(Mb + row * D + col0 + bj * 128), mv);
; #pragma unroll
;                     for (int n = 0; n < 2; ++n)
; #pragma unroll
;                         for (int j = 0; j < 4; ++j) o[4 * n + j] = (first ? 0.f : mv[4 * n + j]) + sigmoidf_(gt[4 * n + j]) * acc[ai][bj][m][n][j];
;                     *(u32x4*)(Mb + row * D + col0 + bj * 128) = pack8(o);
	s_waitcnt lgkmcnt(0)
	s_setprio 1
	s_waitcnt lgkmcnt(0)
	v_mfma_f32_16x16x32_bf16 v[64:67], v[148:151], v[192:195], v[64:67]
	v_mfma_f32_16x16x32_bf16 v[60:63], v[184:187], v[192:195], v[60:63]
	v_mfma_f32_16x16x32_bf16 v[48:51], v[148:151], v[200:203], v[48:51]
	v_mfma_f32_16x16x32_bf16 v[44:47], v[184:187], v[200:203], v[44:47]
	v_mfma_f32_16x16x32_bf16 v[32:35], v[148:151], v[208:211], v[32:35]
	v_mfma_f32_16x16x32_bf16 v[24:27], v[184:187], v[208:211], v[24:27]
	v_mfma_f32_16x16x32_bf16 v[12:15], v[148:151], v[216:219], v[12:15]
	v_mfma_f32_16x16x32_bf16 v[8:11], v[184:187], v[216:219], v[8:11]
	v_mfma_f32_16x16x32_bf16 v[64:67], v[152:155], v[196:199], v[64:67]
	v_mfma_f32_16x16x32_bf16 v[60:63], v[188:191], v[196:199], v[60:63]
	v_mfma_f32_16x16x32_bf16 v[48:51], v[152:155], v[204:207], v[48:51]
	v_mfma_f32_16x16x32_bf16 v[44:47], v[188:191], v[204:207], v[44:47]
	v_mfma_f32_16x16x32_bf16 v[32:35], v[152:155], v[212:215], v[32:35]
	v_mfma_f32_16x16x32_bf16 v[24:27], v[188:191], v[212:215], v[24:27]
	v_mfma_f32_16x16x32_bf16 v[12:15], v[152:155], v[220:223], v[12:15]
	v_mfma_f32_16x16x32_bf16 v[8:11], v[188:191], v[220:223], v[8:11]
	s_setprio 0
	s_barrier
	s_add_u32 s16, s18, 0x40080
	s_addc_u32 s17, s19, 0
	s_mov_b32 m0, s50
	v_lshl_add_u64 v[136:137], s[16:17], 0, v[30:31]
	global_load_lds_dwordx4 v[136:137], off
	v_lshl_add_u64 v[136:137], s[16:17], 0, v[134:135]
	s_mov_b32 m0, s51
	s_nop 0
	global_load_lds_dwordx4 v[136:137], off
	s_waitcnt vmcnt(6)
	s_barrier
	s_setprio 1
	v_mfma_f32_16x16x32_bf16 v[56:59], v[224:227], v[192:195], v[56:59]
	v_mfma_f32_16x16x32_bf16 v[52:55], v[232:235], v[192:195], v[52:55]
	v_mfma_f32_16x16x32_bf16 v[40:43], v[224:227], v[200:203], v[40:43]
	v_mfma_f32_16x16x32_bf16 v[36:39], v[232:235], v[200:203], v[36:39]
	v_mfma_f32_16x16x32_bf16 v[20:23], v[224:227], v[208:211], v[20:23]
	v_mfma_f32_16x16x32_bf16 v[16:19], v[232:235], v[208:211], v[16:19]
	v_mfma_f32_16x16x32_bf16 v[4:7], v[224:227], v[216:219], v[4:7]
	v_mfma_f32_16x16x32_bf16 v[0:3], v[232:235], v[216:219], v[0:3]
	v_mfma_f32_16x16x32_bf16 v[56:59], v[228:231], v[196:199], v[56:59]
	v_mfma_f32_16x16x32_bf16 v[52:55], v[236:239], v[196:199], v[52:55]
	v_mfma_f32_16x16x32_bf16 v[40:43], v[228:231], v[204:207], v[40:43]
	v_mfma_f32_16x16x32_bf16 v[36:39], v[236:239], v[204:207], v[36:39]
	v_mfma_f32_16x16x32_bf16 v[20:23], v[228:231], v[212:215], v[20:23]
	v_mfma_f32_16x16x32_bf16 v[16:19], v[236:239], v[212:215], v[16:19]
	v_mfma_f32_16x16x32_bf16 v[4:7], v[228:231], v[220:223], v[4:7]
	v_mfma_f32_16x16x32_bf16 v[0:3], v[236:239], v[220:223], v[0:3]
	s_setprio 0
	s_add_i32 s59, s59, 2
	s_add_u32 s57, s57, 0x100
	s_addc_u32 s58, s58, 0
	s_cmp_gt_u32 s59, 13
	s_mov_b64 s[16:17], s[4:5]
	s_barrier
	s_cbranch_scc0 .LBB0_1863
	v_lshl_or_b32 v136, s55, 8, v158
	v_lshl_add_u32 v152, s0, 8, v156
	v_lshlrev_b32_e32 v234, 1, v136
	v_mad_u32_u24 v232, v152, s33, v234
	v_add_u32_e32 v232, 0x1800, v232
	v_lshl_add_u32 v233, v152, 11, v234
	v_mov_b32_e32 v235, v232
	v_add_u32_e32 v236, 0x42000, v232
	global_load_dwordx4 v[200:203], v235, s[8:9]
	global_load_dwordx4 v[204:207], v235, s[8:9] offset:256
	global_load_dwordx4 v[208:211], v236, s[8:9]
	global_load_dwordx4 v[212:215], v236, s[8:9] offset:256
	v_mov_b32_e32 v235, v233
	v_add_u32_e32 v236, 0x8000, v233
	global_load_dwordx4 v[216:219], v235, s[6:7]
	global_load_dwordx4 v[220:223], v235, s[6:7] offset:256
	global_load_dwordx4 v[224:227], v236, s[6:7]
	global_load_dwordx4 v[228:231], v236, s[6:7] offset:256
	s_waitcnt vmcnt(0)
	v_ashrrev_i32_e32 v137, 31, v136
	v_mov_b64_e32 v[150:151], s[8:9]
	v_mad_i64_i32 v[154:155], s[4:5], v152, s33, v[150:151]
	v_lshlrev_b64 v[148:149], 1, v[136:137]
	v_lshl_add_u64 v[136:137], v[154:155], 0, v[148:149]
	s_mov_b64 s[16:17], 0x1800
	v_lshl_add_u64 v[160:161], v[136:137], 0, s[16:17]
	v_add_co_u32_e32 v136, vcc, 0x1000, v136
	v_ashrrev_i32_e32 v153, 31, v152
	s_nop 0
	v_addc_co_u32_e32 v137, vcc, 0, v137, vcc
	s_nop 1
	v_mov_b64_e32 v[184:185], v[200:201]
	v_mov_b64_e32 v[186:187], v[202:203]
	v_lshlrev_b64 v[138:139], 11, v[152:153]
	v_lshl_add_u64 v[136:137], s[6:7], 0, v[138:139]
	v_lshl_add_u64 v[154:155], v[136:137], 0, v[148:149]
	s_movk_i32 s0, 0x1000
	s_mov_b32 s55, s10
	s_mov_b64 s[18:19], s[14:15]
	v_lshlrev_b32_e32 v153, 16, v184
	v_and_b32_e32 v188, 0xffff0000, v184
	v_lshlrev_b32_e32 v189, 16, v185
	v_and_b32_e32 v190, 0xffff0000, v185
	v_lshlrev_b32_e32 v191, 16, v186
	v_and_b32_e32 v192, 0xffff0000, v186
	v_lshlrev_b32_e32 v193, 16, v187
	v_and_b32_e32 v194, 0xffff0000, v187
	s_nop 1
	v_mov_b64_e32 v[184:185], v[216:217]
	v_mov_b64_e32 v[186:187], v[218:219]
	v_mul_f32_e32 v136, 0xbfb8aa3b, v153
	v_mul_f32_e32 v137, 0xbfb8aa3b, v188
	v_exp_f32_e32 v136, v136
	v_exp_f32_e32 v137, v137
	v_add_f32_e32 v136, 1.0, v136
	v_add_f32_e32 v137, 1.0, v137
	v_rcp_f32_e32 v136, v136
	v_rcp_f32_e32 v137, v137
	v_lshlrev_b32_e32 v138, 16, v184
	v_and_b32_e32 v139, 0xffff0000, v184
	v_pk_fma_f32 v[128:129], v[128:129], v[136:137], v[138:139]
	v_mul_f32_e32 v136, 0xbfb8aa3b, v189
	v_mul_f32_e32 v137, 0xbfb8aa3b, v190
	v_exp_f32_e32 v136, v136
	v_exp_f32_e32 v137, v137
	v_lshlrev_b32_e32 v138, 16, v185
	v_and_b32_e32 v139, 0xffff0000, v185
	v_add_f32_e32 v136, 1.0, v136
	v_add_f32_e32 v137, 1.0, v137
	v_rcp_f32_e32 v136, v136
	v_rcp_f32_e32 v137, v137
	s_nop 0
	v_pk_fma_f32 v[130:131], v[130:131], v[136:137], v[138:139]
	v_mul_f32_e32 v136, 0xbfb8aa3b, v191
	v_mul_f32_e32 v137, 0xbfb8aa3b, v192
	v_exp_f32_e32 v136, v136
	v_exp_f32_e32 v137, v137
	v_lshlrev_b32_e32 v138, 16, v186
	v_and_b32_e32 v139, 0xffff0000, v186
	v_add_f32_e32 v136, 1.0, v136
; __device__ __forceinline__ void unpack8(const u32x4 w, float (&f)[8]) { f[0] = bflo(w.x); f[1] = bfhi(w.x); f[2] = bflo(w.y); f[3] = bfhi(w.y); f[4] = bflo(w.z); f[5] = bfhi(w.z); f[6] = bflo(w.w); f[7] = bfhi(w.w); }
; __device__ __forceinline__ u32x4 pack8(const float (&f)[8]) { u32x4 w; w.x = pk2(f[0], f[1]); w.y = pk2(f[2], f[3]); w.z = pk2(f[4], f[5]); w.w = pk2(f[6], f[7]); return w; }
; __device__ __forceinline__ float sigmoidf_(float x) { return __builtin_amdgcn_rcpf(1.0f + __expf(-x)); }
;     __device__ __forceinline__ void operator()(const f32x4 (&acc)[2][2][4][2], const pg8::Unit& u, int wr, int wc, int fr, int fq) const {
;     ...
;                 const size_t row = (size_t)(row0 + ai * 128 + m * 16);
; #pragma unroll
;                 for (int bj = 0; bj < 2; ++bj) {
;                     float gt[8], mv[8], o[8];
;                     unpack8(*(const u32x4*)(Z + row * ZW + goff + col0 + bj * 128), gt);
;                     if (!first) unpack8(*(const u32x4*)(Mb + row * D + col0 + bj * 128), mv);
; #pragma unroll
;                     for (int n = 0; n < 2; ++n)
; #pragma unroll
;                         for (int j = 0; j < 4; ++j) o[4 * n + j] = (first ? 0.f : mv[4 * n + j]) + sigmoidf_(gt[4 * n + j]) * acc[ai][bj][m][n][j];
;                     *(u32x4*)(Mb + row * D + col0 + bj * 128) = pack8(o);
	v_add_f32_e32 v137, 1.0, v137
	v_rcp_f32_e32 v136, v136
	v_rcp_f32_e32 v137, v137
	s_nop 0
	v_pk_fma_f32 v[136:137], v[124:125], v[136:137], v[138:139]
	v_mul_f32_e32 v124, 0xbfb8aa3b, v193
	v_mul_f32_e32 v125, 0xbfb8aa3b, v194
	v_exp_f32_e32 v124, v124
	v_exp_f32_e32 v125, v125
	v_lshlrev_b32_e32 v138, 16, v187
	v_and_b32_e32 v139, 0xffff0000, v187
	v_add_f32_e32 v124, 1.0, v124
	v_add_f32_e32 v125, 1.0, v125
	v_rcp_f32_e32 v124, v124
	v_rcp_f32_e32 v125, v125
	s_nop 0
	v_pk_fma_f32 v[138:139], v[126:127], v[124:125], v[138:139]
	v_cvt_pk_bf16_f32 v124, v128, v129
	v_cvt_pk_bf16_f32 v125, v130, v131
	v_cvt_pk_bf16_f32 v126, v136, v137
	v_cvt_pk_bf16_f32 v127, v138, v139
	global_store_dwordx4 v[154:155], v[124:127], off
	s_nop 1
	v_mov_b64_e32 v[124:125], v[204:205]
	v_mov_b64_e32 v[126:127], v[206:207]
	v_lshlrev_b32_e32 v128, 16, v124
	v_and_b32_e32 v129, 0xffff0000, v124
	v_lshlrev_b32_e32 v136, 16, v125
	v_and_b32_e32 v137, 0xffff0000, v125
	v_lshlrev_b32_e32 v138, 16, v126
	v_and_b32_e32 v139, 0xffff0000, v126
	v_lshlrev_b32_e32 v153, 16, v127
	v_and_b32_e32 v160, 0xffff0000, v127
	s_nop 1
	v_mov_b64_e32 v[124:125], v[220:221]
	v_mov_b64_e32 v[126:127], v[222:223]
	v_mul_f32_e32 v128, 0xbfb8aa3b, v128
	v_mul_f32_e32 v129, 0xbfb8aa3b, v129
	v_exp_f32_e32 v128, v128
	v_exp_f32_e32 v129, v129
	v_add_f32_e32 v128, 1.0, v128
	v_add_f32_e32 v129, 1.0, v129
	v_rcp_f32_e32 v128, v128
	v_rcp_f32_e32 v129, v129
	v_lshlrev_b32_e32 v130, 16, v124
	v_and_b32_e32 v131, 0xffff0000, v124
	v_mul_f32_e32 v124, 0xbfb8aa3b, v136
	v_exp_f32_e32 v124, v124
	v_pk_fma_f32 v[120:121], v[120:121], v[128:129], v[130:131]
	v_add_f32_e32 v124, 1.0, v124
	v_rcp_f32_e32 v128, v124
	v_mul_f32_e32 v124, 0xbfb8aa3b, v137
	v_exp_f32_e32 v124, v124
	s_nop 0
	v_add_f32_e32 v124, 1.0, v124
	v_rcp_f32_e32 v129, v124
	v_lshlrev_b32_e32 v124, 16, v125
	v_and_b32_e32 v125, 0xffff0000, v125
	v_pk_fma_f32 v[122:123], v[122:123], v[128:129], v[124:125]
	v_mul_f32_e32 v124, 0xbfb8aa3b, v138
	v_mul_f32_e32 v125, 0xbfb8aa3b, v139
	v_exp_f32_e32 v124, v124
	v_exp_f32_e32 v125, v125
	v_lshlrev_b32_e32 v128, 16, v126
	v_and_b32_e32 v129, 0xffff0000, v126
	v_add_f32_e32 v124, 1.0, v124
	v_add_f32_e32 v125, 1.0, v125
	v_rcp_f32_e32 v124, v124
	v_rcp_f32_e32 v125, v125
	v_lshlrev_b32_e32 v126, 16, v127
	v_and_b32_e32 v127, 0xffff0000, v127
	v_pk_fma_f32 v[124:125], v[116:117], v[124:125], v[128:129]
	v_mul_f32_e32 v116, 0xbfb8aa3b, v153
	v_mul_f32_e32 v117, 0xbfb8aa3b, v160
	v_exp_f32_e32 v116, v116
	v_exp_f32_e32 v117, v117
	v_add_f32_e32 v116, 1.0, v116
	v_add_f32_e32 v117, 1.0, v117
	v_rcp_f32_e32 v116, v116
	v_rcp_f32_e32 v117, v117
	s_nop 0
	v_pk_fma_f32 v[126:127], v[118:119], v[116:117], v[126:127]
	v_cvt_pk_bf16_f32 v116, v120, v121
	v_cvt_pk_bf16_f32 v117, v122, v123
	v_cvt_pk_bf16_f32 v118, v124, v125
	v_cvt_pk_bf16_f32 v119, v126, v127
	global_store_dwordx4 v[154:155], v[116:119], off offset:256
	s_nop 1
	v_or_b32_e32 v116, 16, v152
	v_ashrrev_i32_e32 v117, 31, v116
	v_lshlrev_b64 v[124:125], 11, v[116:117]
	v_mad_i64_i32 v[116:117], s[4:5], v116, s33, v[150:151]
	v_lshl_add_u64 v[116:117], v[116:117], 0, v[148:149]
	v_lshl_add_u64 v[118:119], v[116:117], 0, s[16:17]
	v_add_co_u32_e32 v116, vcc, s0, v116
	s_nop 1
	v_addc_co_u32_e32 v117, vcc, 0, v117, vcc
	s_nop 1
	v_mov_b64_e32 v[120:121], v[208:209]
	v_mov_b64_e32 v[122:123], v[210:211]
	v_lshl_add_u64 v[116:117], s[6:7], 0, v[124:125]
	v_lshl_add_u64 v[116:117], v[116:117], 0, v[148:149]
	v_lshlrev_b32_e32 v126, 16, v120
	v_and_b32_e32 v127, 0xffff0000, v120
	v_lshlrev_b32_e32 v128, 16, v121
	v_and_b32_e32 v129, 0xffff0000, v121
	v_lshlrev_b32_e32 v130, 16, v122
	v_and_b32_e32 v131, 0xffff0000, v122
	v_lshlrev_b32_e32 v136, 16, v123
	v_and_b32_e32 v137, 0xffff0000, v123
	s_nop 1
	v_mov_b64_e32 v[120:121], v[224:225]
	v_mov_b64_e32 v[122:123], v[226:227]
	v_mul_f32_e32 v124, 0xbfb8aa3b, v126
	v_mul_f32_e32 v125, 0xbfb8aa3b, v127
	v_exp_f32_e32 v124, v124
	v_exp_f32_e32 v125, v125
	v_add_f32_e32 v124, 1.0, v124
	v_add_f32_e32 v125, 1.0, v125
	v_rcp_f32_e32 v124, v124
	v_rcp_f32_e32 v125, v125
	v_lshlrev_b32_e32 v126, 16, v120
	v_and_b32_e32 v127, 0xffff0000, v120
	v_mul_f32_e32 v120, 0xbfb8aa3b, v128
	v_exp_f32_e32 v120, v120
	v_pk_fma_f32 v[112:113], v[112:113], v[124:125], v[126:127]
	v_add_f32_e32 v120, 1.0, v120
	v_rcp_f32_e32 v124, v120
	v_mul_f32_e32 v120, 0xbfb8aa3b, v129
	v_exp_f32_e32 v120, v120
	s_nop 0
	v_add_f32_e32 v120, 1.0, v120
	v_rcp_f32_e32 v125, v120
	v_lshlrev_b32_e32 v120, 16, v121
	v_and_b32_e32 v121, 0xffff0000, v121
	v_pk_fma_f32 v[114:115], v[114:115], v[124:125], v[120:121]
	v_mul_f32_e32 v120, 0xbfb8aa3b, v130
	v_mul_f32_e32 v121, 0xbfb8aa3b, v131
	v_exp_f32_e32 v120, v120
	v_exp_f32_e32 v121, v121
	v_lshlrev_b32_e32 v124, 16, v122
	v_and_b32_e32 v125, 0xffff0000, v122
	v_add_f32_e32 v120, 1.0, v120
	v_add_f32_e32 v121, 1.0, v121
	v_rcp_f32_e32 v120, v120
	v_rcp_f32_e32 v121, v121
	v_lshlrev_b32_e32 v122, 16, v123
	v_and_b32_e32 v123, 0xffff0000, v123
	v_pk_fma_f32 v[120:121], v[108:109], v[120:121], v[124:125]
	v_mul_f32_e32 v108, 0xbfb8aa3b, v136
	v_mul_f32_e32 v109, 0xbfb8aa3b, v137
	v_exp_f32_e32 v108, v108
	v_exp_f32_e32 v109, v109
	v_add_f32_e32 v108, 1.0, v108
	v_add_f32_e32 v109, 1.0, v109
	v_rcp_f32_e32 v108, v108
	v_rcp_f32_e32 v109, v109
	s_nop 0
	v_pk_fma_f32 v[122:123], v[110:111], v[108:109], v[122:123]
	v_cvt_pk_bf16_f32 v108, v112, v113
	v_cvt_pk_bf16_f32 v109, v114, v115
	v_cvt_pk_bf16_f32 v110, v120, v121
	v_cvt_pk_bf16_f32 v111, v122, v123
	global_store_dwordx4 v[116:117], v[108:111], off
	s_nop 1
	v_mov_b64_e32 v[108:109], v[212:213]
	v_mov_b64_e32 v[110:111], v[214:215]
; __device__ __forceinline__ void unpack8(const u32x4 w, float (&f)[8]) { f[0] = bflo(w.x); f[1] = bfhi(w.x); f[2] = bflo(w.y); f[3] = bfhi(w.y); f[4] = bflo(w.z); f[5] = bfhi(w.z); f[6] = bflo(w.w); f[7] = bfhi(w.w); }
; __device__ __forceinline__ u32x4 pack8(const float (&f)[8]) { u32x4 w; w.x = pk2(f[0], f[1]); w.y = pk2(f[2], f[3]); w.z = pk2(f[4], f[5]); w.w = pk2(f[6], f[7]); return w; }
; __device__ __forceinline__ float sigmoidf_(float x) { return __builtin_amdgcn_rcpf(1.0f + __expf(-x)); }
;     __device__ __forceinline__ void operator()(const f32x4 (&acc)[2][2][4][2], const pg8::Unit& u, int wr, int wc, int fr, int fq) const {
;     ...
;                 const size_t row = (size_t)(row0 + ai * 128 + m * 16);
; #pragma unroll
;                 for (int bj = 0; bj < 2; ++bj) {
;                     float gt[8], mv[8], o[8];
;                     unpack8(*(const u32x4*)(Z + row * ZW + goff + col0 + bj * 128), gt);
;                     if (!first) unpack8(*(const u32x4*)(Mb + row * D + col0 + bj * 128), mv);
; #pragma unroll
;                     for (int n = 0; n < 2; ++n)
; #pragma unroll
;                         for (int j = 0; j < 4; ++j) o[4 * n + j] = (first ? 0.f : mv[4 * n + j]) + sigmoidf_(gt[4 * n + j]) * acc[ai][bj][m][n][j];
;                     *(u32x4*)(Mb + row * D + col0 + bj * 128) = pack8(o);
	v_lshlrev_b32_e32 v112, 16, v108
	v_and_b32_e32 v113, 0xffff0000, v108
	v_lshlrev_b32_e32 v118, 16, v109
	v_and_b32_e32 v119, 0xffff0000, v109
	v_lshlrev_b32_e32 v120, 16, v110
	v_and_b32_e32 v121, 0xffff0000, v110
	v_lshlrev_b32_e32 v122, 16, v111
	v_and_b32_e32 v123, 0xffff0000, v111
	s_nop 1
	v_mov_b64_e32 v[108:109], v[228:229]
	v_mov_b64_e32 v[110:111], v[230:231]
	v_mul_f32_e32 v112, 0xbfb8aa3b, v112
	v_mul_f32_e32 v113, 0xbfb8aa3b, v113
	v_exp_f32_e32 v112, v112
	v_exp_f32_e32 v113, v113
	v_add_f32_e32 v112, 1.0, v112
	v_add_f32_e32 v113, 1.0, v113
	v_rcp_f32_e32 v112, v112
	v_rcp_f32_e32 v113, v113
	v_lshlrev_b32_e32 v114, 16, v108
	v_and_b32_e32 v115, 0xffff0000, v108
	v_mul_f32_e32 v108, 0xbfb8aa3b, v118
	v_exp_f32_e32 v108, v108
	v_pk_fma_f32 v[104:105], v[104:105], v[112:113], v[114:115]
	v_add_f32_e32 v108, 1.0, v108
	v_rcp_f32_e32 v112, v108
	v_mul_f32_e32 v108, 0xbfb8aa3b, v119
	v_exp_f32_e32 v108, v108
	s_nop 0
	v_add_f32_e32 v108, 1.0, v108
	v_rcp_f32_e32 v113, v108
	v_lshlrev_b32_e32 v108, 16, v109
	v_and_b32_e32 v109, 0xffff0000, v109
	v_pk_fma_f32 v[106:107], v[106:107], v[112:113], v[108:109]
	v_mul_f32_e32 v108, 0xbfb8aa3b, v120
	v_mul_f32_e32 v109, 0xbfb8aa3b, v121
	v_exp_f32_e32 v108, v108
	v_exp_f32_e32 v109, v109
	v_lshlrev_b32_e32 v112, 16, v110
	v_and_b32_e32 v113, 0xffff0000, v110
	v_add_f32_e32 v108, 1.0, v108
	v_add_f32_e32 v109, 1.0, v109
	v_rcp_f32_e32 v108, v108
	v_rcp_f32_e32 v109, v109
	v_lshlrev_b32_e32 v110, 16, v111
	v_and_b32_e32 v111, 0xffff0000, v111
	v_pk_fma_f32 v[108:109], v[100:101], v[108:109], v[112:113]
	v_mul_f32_e32 v100, 0xbfb8aa3b, v122
	v_mul_f32_e32 v101, 0xbfb8aa3b, v123
	v_exp_f32_e32 v100, v100
	v_exp_f32_e32 v101, v101
	v_add_f32_e32 v100, 1.0, v100
	v_add_f32_e32 v101, 1.0, v101
	v_rcp_f32_e32 v100, v100
	v_rcp_f32_e32 v101, v101
	s_nop 0
	v_pk_fma_f32 v[110:111], v[102:103], v[100:101], v[110:111]
	v_cvt_pk_bf16_f32 v100, v104, v105
	v_cvt_pk_bf16_f32 v101, v106, v107
	v_cvt_pk_bf16_f32 v102, v108, v109
	v_cvt_pk_bf16_f32 v103, v110, v111
	global_store_dwordx4 v[116:117], v[100:103], off offset:256
	s_nop 1
	v_add_u32_e32 v235, 0x84000, v232
	v_add_u32_e32 v236, 0xc6000, v232
	global_load_dwordx4 v[200:203], v235, s[8:9]
	global_load_dwordx4 v[204:207], v235, s[8:9] offset:256
	global_load_dwordx4 v[208:211], v236, s[8:9]
	global_load_dwordx4 v[212:215], v236, s[8:9] offset:256
	v_add_u32_e32 v235, 0x10000, v233
	v_add_u32_e32 v236, 0x18000, v233
	global_load_dwordx4 v[216:219], v235, s[6:7]
	global_load_dwordx4 v[220:223], v235, s[6:7] offset:256
	global_load_dwordx4 v[224:227], v236, s[6:7]
	global_load_dwordx4 v[228:231], v236, s[6:7] offset:256
	s_waitcnt vmcnt(0)
	v_or_b32_e32 v100, 32, v152
	v_ashrrev_i32_e32 v101, 31, v100
	v_lshlrev_b64 v[106:107], 11, v[100:101]
	v_mad_i64_i32 v[100:101], s[4:5], v100, s33, v[150:151]
	v_lshl_add_u64 v[102:103], v[100:101], 0, v[148:149]
	v_lshl_add_u64 v[100:101], v[102:103], 0, s[16:17]
	v_add_co_u32_e32 v102, vcc, s0, v102
	s_nop 1
	v_addc_co_u32_e32 v103, vcc, 0, v103, vcc
	s_nop 1
	v_mov_b64_e32 v[102:103], v[200:201]
	v_mov_b64_e32 v[104:105], v[202:203]
	v_lshlrev_b32_e32 v108, 16, v102
	v_and_b32_e32 v109, 0xffff0000, v102
	v_lshlrev_b32_e32 v112, 16, v103
	v_and_b32_e32 v113, 0xffff0000, v103
	v_lshl_add_u64 v[102:103], s[6:7], 0, v[106:107]
	v_lshl_add_u64 v[102:103], v[102:103], 0, v[148:149]
	v_lshlrev_b32_e32 v114, 16, v104
	v_and_b32_e32 v115, 0xffff0000, v104
	v_lshlrev_b32_e32 v116, 16, v105
	v_and_b32_e32 v117, 0xffff0000, v105
	s_nop 1
	v_mov_b64_e32 v[104:105], v[216:217]
	v_mov_b64_e32 v[106:107], v[218:219]
	v_mul_f32_e32 v108, 0xbfb8aa3b, v108
	v_mul_f32_e32 v109, 0xbfb8aa3b, v109
	v_exp_f32_e32 v108, v108
	v_exp_f32_e32 v109, v109
	v_add_f32_e32 v108, 1.0, v108
	v_add_f32_e32 v109, 1.0, v109
	v_rcp_f32_e32 v108, v108
	v_rcp_f32_e32 v109, v109
	v_lshlrev_b32_e32 v110, 16, v104
	v_and_b32_e32 v111, 0xffff0000, v104
	v_mul_f32_e32 v104, 0xbfb8aa3b, v112
	v_exp_f32_e32 v104, v104
	v_pk_fma_f32 v[96:97], v[96:97], v[108:109], v[110:111]
	v_add_f32_e32 v104, 1.0, v104
	v_rcp_f32_e32 v108, v104
	v_mul_f32_e32 v104, 0xbfb8aa3b, v113
	v_exp_f32_e32 v104, v104
	s_nop 0
	v_add_f32_e32 v104, 1.0, v104
	v_rcp_f32_e32 v109, v104
	v_lshlrev_b32_e32 v104, 16, v105
	v_and_b32_e32 v105, 0xffff0000, v105
	v_pk_fma_f32 v[98:99], v[98:99], v[108:109], v[104:105]
	v_mul_f32_e32 v104, 0xbfb8aa3b, v114
	v_mul_f32_e32 v105, 0xbfb8aa3b, v115
	v_exp_f32_e32 v104, v104
	v_exp_f32_e32 v105, v105
	v_lshlrev_b32_e32 v108, 16, v106
	v_and_b32_e32 v109, 0xffff0000, v106
	v_add_f32_e32 v104, 1.0, v104
	v_add_f32_e32 v105, 1.0, v105
	v_rcp_f32_e32 v104, v104
	v_rcp_f32_e32 v105, v105
	v_lshlrev_b32_e32 v106, 16, v107
	v_and_b32_e32 v107, 0xffff0000, v107
	v_pk_fma_f32 v[104:105], v[92:93], v[104:105], v[108:109]
	v_mul_f32_e32 v92, 0xbfb8aa3b, v116
	v_mul_f32_e32 v93, 0xbfb8aa3b, v117
	v_exp_f32_e32 v92, v92
	v_exp_f32_e32 v93, v93
	v_add_f32_e32 v92, 1.0, v92
	v_add_f32_e32 v93, 1.0, v93
	v_rcp_f32_e32 v92, v92
	v_rcp_f32_e32 v93, v93
	s_nop 0
	v_pk_fma_f32 v[106:107], v[94:95], v[92:93], v[106:107]
	v_cvt_pk_bf16_f32 v92, v96, v97
	v_cvt_pk_bf16_f32 v93, v98, v99
	v_cvt_pk_bf16_f32 v94, v104, v105
	v_cvt_pk_bf16_f32 v95, v106, v107
	global_store_dwordx4 v[102:103], v[92:95], off
	s_nop 1
	v_mov_b64_e32 v[92:93], v[204:205]
	v_mov_b64_e32 v[94:95], v[206:207]
	v_lshlrev_b32_e32 v96, 16, v92
	v_and_b32_e32 v97, 0xffff0000, v92
	v_lshlrev_b32_e32 v100, 16, v93
	v_and_b32_e32 v101, 0xffff0000, v93
	v_lshlrev_b32_e32 v104, 16, v94
	v_and_b32_e32 v105, 0xffff0000, v94
	v_lshlrev_b32_e32 v106, 16, v95
	v_and_b32_e32 v107, 0xffff0000, v95
	s_nop 1
; __device__ __forceinline__ void unpack8(const u32x4 w, float (&f)[8]) { f[0] = bflo(w.x); f[1] = bfhi(w.x); f[2] = bflo(w.y); f[3] = bfhi(w.y); f[4] = bflo(w.z); f[5] = bfhi(w.z); f[6] = bflo(w.w); f[7] = bfhi(w.w); }
; __device__ __forceinline__ u32x4 pack8(const float (&f)[8]) { u32x4 w; w.x = pk2(f[0], f[1]); w.y = pk2(f[2], f[3]); w.z = pk2(f[4], f[5]); w.w = pk2(f[6], f[7]); return w; }
; __device__ __forceinline__ float sigmoidf_(float x) { return __builtin_amdgcn_rcpf(1.0f + __expf(-x)); }
;     __device__ __forceinline__ void operator()(const f32x4 (&acc)[2][2][4][2], const pg8::Unit& u, int wr, int wc, int fr, int fq) const {
;     ...
;                 const size_t row = (size_t)(row0 + ai * 128 + m * 16);
; #pragma unroll
;                 for (int bj = 0; bj < 2; ++bj) {
;                     float gt[8], mv[8], o[8];
;                     unpack8(*(const u32x4*)(Z + row * ZW + goff + col0 + bj * 128), gt);
;                     if (!first) unpack8(*(const u32x4*)(Mb + row * D + col0 + bj * 128), mv);
; #pragma unroll
;                     for (int n = 0; n < 2; ++n)
; #pragma unroll
;                         for (int j = 0; j < 4; ++j) o[4 * n + j] = (first ? 0.f : mv[4 * n + j]) + sigmoidf_(gt[4 * n + j]) * acc[ai][bj][m][n][j];
;                     *(u32x4*)(Mb + row * D + col0 + bj * 128) = pack8(o);
	v_mov_b64_e32 v[92:93], v[220:221]
	v_mov_b64_e32 v[94:95], v[222:223]
	v_mul_f32_e32 v96, 0xbfb8aa3b, v96
	v_mul_f32_e32 v97, 0xbfb8aa3b, v97
	v_exp_f32_e32 v96, v96
	v_exp_f32_e32 v97, v97
	v_add_f32_e32 v96, 1.0, v96
	v_add_f32_e32 v97, 1.0, v97
	v_rcp_f32_e32 v96, v96
	v_rcp_f32_e32 v97, v97
	v_lshlrev_b32_e32 v98, 16, v92
	v_and_b32_e32 v99, 0xffff0000, v92
	v_mul_f32_e32 v92, 0xbfb8aa3b, v100
	v_exp_f32_e32 v92, v92
	v_pk_fma_f32 v[88:89], v[88:89], v[96:97], v[98:99]
	v_add_f32_e32 v92, 1.0, v92
	v_rcp_f32_e32 v96, v92
	v_mul_f32_e32 v92, 0xbfb8aa3b, v101
	v_exp_f32_e32 v92, v92
	s_nop 0
	v_add_f32_e32 v92, 1.0, v92
	v_rcp_f32_e32 v97, v92
	v_lshlrev_b32_e32 v92, 16, v93
	v_and_b32_e32 v93, 0xffff0000, v93
	v_pk_fma_f32 v[90:91], v[90:91], v[96:97], v[92:93]
	v_mul_f32_e32 v92, 0xbfb8aa3b, v104
	v_mul_f32_e32 v93, 0xbfb8aa3b, v105
	v_exp_f32_e32 v92, v92
	v_exp_f32_e32 v93, v93
	v_lshlrev_b32_e32 v96, 16, v94
	v_and_b32_e32 v97, 0xffff0000, v94
	v_add_f32_e32 v92, 1.0, v92
	v_add_f32_e32 v93, 1.0, v93
	v_rcp_f32_e32 v92, v92
	v_rcp_f32_e32 v93, v93
	v_lshlrev_b32_e32 v94, 16, v95
	v_and_b32_e32 v95, 0xffff0000, v95
	v_pk_fma_f32 v[92:93], v[84:85], v[92:93], v[96:97]
	v_mul_f32_e32 v84, 0xbfb8aa3b, v106
	v_mul_f32_e32 v85, 0xbfb8aa3b, v107
	v_exp_f32_e32 v84, v84
	v_exp_f32_e32 v85, v85
	v_add_f32_e32 v84, 1.0, v84
	v_add_f32_e32 v85, 1.0, v85
	v_rcp_f32_e32 v84, v84
	v_rcp_f32_e32 v85, v85
	s_nop 0
	v_pk_fma_f32 v[94:95], v[86:87], v[84:85], v[94:95]
	v_cvt_pk_bf16_f32 v84, v88, v89
	v_cvt_pk_bf16_f32 v85, v90, v91
	v_cvt_pk_bf16_f32 v86, v92, v93
	v_cvt_pk_bf16_f32 v87, v94, v95
	global_store_dwordx4 v[102:103], v[84:87], off offset:256
	s_nop 1
	v_or_b32_e32 v84, 48, v152
	v_ashrrev_i32_e32 v85, 31, v84
	v_lshlrev_b64 v[90:91], 11, v[84:85]
	v_mad_i64_i32 v[84:85], s[4:5], v84, s33, v[150:151]
	v_lshl_add_u64 v[86:87], v[84:85], 0, v[148:149]
	v_lshl_add_u64 v[84:85], v[86:87], 0, s[16:17]
	v_add_co_u32_e32 v86, vcc, s0, v86
	s_nop 1
	v_addc_co_u32_e32 v87, vcc, 0, v87, vcc
	s_nop 1
	v_mov_b64_e32 v[86:87], v[208:209]
	v_mov_b64_e32 v[88:89], v[210:211]
	v_lshlrev_b32_e32 v92, 16, v86
	v_and_b32_e32 v93, 0xffff0000, v86
	v_lshlrev_b32_e32 v96, 16, v87
	v_and_b32_e32 v97, 0xffff0000, v87
	v_lshl_add_u64 v[86:87], s[6:7], 0, v[90:91]
	v_lshl_add_u64 v[86:87], v[86:87], 0, v[148:149]
	v_lshlrev_b32_e32 v98, 16, v88
	v_and_b32_e32 v99, 0xffff0000, v88
	v_lshlrev_b32_e32 v100, 16, v89
	v_and_b32_e32 v101, 0xffff0000, v89
	s_nop 1
	v_mov_b64_e32 v[88:89], v[224:225]
	v_mov_b64_e32 v[90:91], v[226:227]
	v_mul_f32_e32 v92, 0xbfb8aa3b, v92
	v_mul_f32_e32 v93, 0xbfb8aa3b, v93
	v_exp_f32_e32 v92, v92
	v_exp_f32_e32 v93, v93
	v_add_f32_e32 v92, 1.0, v92
	v_add_f32_e32 v93, 1.0, v93
	v_rcp_f32_e32 v92, v92
	v_rcp_f32_e32 v93, v93
	v_lshlrev_b32_e32 v94, 16, v88
	v_and_b32_e32 v95, 0xffff0000, v88
	v_mul_f32_e32 v88, 0xbfb8aa3b, v96
	v_exp_f32_e32 v88, v88
	v_pk_fma_f32 v[80:81], v[80:81], v[92:93], v[94:95]
	v_add_f32_e32 v88, 1.0, v88
	v_rcp_f32_e32 v92, v88
	v_mul_f32_e32 v88, 0xbfb8aa3b, v97
	v_exp_f32_e32 v88, v88
	s_nop 0
	v_add_f32_e32 v88, 1.0, v88
	v_rcp_f32_e32 v93, v88
	v_lshlrev_b32_e32 v88, 16, v89
	v_and_b32_e32 v89, 0xffff0000, v89
	v_pk_fma_f32 v[82:83], v[82:83], v[92:93], v[88:89]
	v_mul_f32_e32 v88, 0xbfb8aa3b, v98
	v_mul_f32_e32 v89, 0xbfb8aa3b, v99
	v_exp_f32_e32 v88, v88
	v_exp_f32_e32 v89, v89
	v_lshlrev_b32_e32 v92, 16, v90
	v_and_b32_e32 v93, 0xffff0000, v90
	v_add_f32_e32 v88, 1.0, v88
	v_add_f32_e32 v89, 1.0, v89
	v_rcp_f32_e32 v88, v88
	v_rcp_f32_e32 v89, v89
	v_lshlrev_b32_e32 v90, 16, v91
	v_and_b32_e32 v91, 0xffff0000, v91
	v_pk_fma_f32 v[88:89], v[76:77], v[88:89], v[92:93]
	v_mul_f32_e32 v76, 0xbfb8aa3b, v100
	v_mul_f32_e32 v77, 0xbfb8aa3b, v101
	v_exp_f32_e32 v76, v76
	v_exp_f32_e32 v77, v77
	v_add_f32_e32 v76, 1.0, v76
	v_add_f32_e32 v77, 1.0, v77
	v_rcp_f32_e32 v76, v76
	v_rcp_f32_e32 v77, v77
	s_nop 0
	v_pk_fma_f32 v[90:91], v[78:79], v[76:77], v[90:91]
	v_cvt_pk_bf16_f32 v76, v80, v81
	v_cvt_pk_bf16_f32 v77, v82, v83
	v_cvt_pk_bf16_f32 v78, v88, v89
	v_cvt_pk_bf16_f32 v79, v90, v91
	global_store_dwordx4 v[86:87], v[76:79], off
	s_nop 1
	v_mov_b64_e32 v[76:77], v[212:213]
	v_mov_b64_e32 v[78:79], v[214:215]
	v_lshlrev_b32_e32 v80, 16, v76
	v_and_b32_e32 v81, 0xffff0000, v76
	v_lshlrev_b32_e32 v84, 16, v77
	v_and_b32_e32 v85, 0xffff0000, v77
	v_lshlrev_b32_e32 v88, 16, v78
	v_and_b32_e32 v89, 0xffff0000, v78
	v_lshlrev_b32_e32 v90, 16, v79
	v_and_b32_e32 v91, 0xffff0000, v79
	s_nop 1
	v_mov_b64_e32 v[76:77], v[228:229]
	v_mov_b64_e32 v[78:79], v[230:231]
	v_mul_f32_e32 v80, 0xbfb8aa3b, v80
	v_mul_f32_e32 v81, 0xbfb8aa3b, v81
	v_exp_f32_e32 v80, v80
	v_exp_f32_e32 v81, v81
	v_add_f32_e32 v80, 1.0, v80
	v_add_f32_e32 v81, 1.0, v81
	v_rcp_f32_e32 v80, v80
	v_rcp_f32_e32 v81, v81
	v_lshlrev_b32_e32 v82, 16, v76
	v_and_b32_e32 v83, 0xffff0000, v76
	v_mul_f32_e32 v76, 0xbfb8aa3b, v84
	v_exp_f32_e32 v76, v76
	v_pk_fma_f32 v[72:73], v[72:73], v[80:81], v[82:83]
	v_add_f32_e32 v76, 1.0, v76
	v_rcp_f32_e32 v80, v76
	v_mul_f32_e32 v76, 0xbfb8aa3b, v85
	v_exp_f32_e32 v76, v76
	s_nop 0
	v_add_f32_e32 v76, 1.0, v76
	v_rcp_f32_e32 v81, v76
	v_lshlrev_b32_e32 v76, 16, v77
	v_and_b32_e32 v77, 0xffff0000, v77
	v_pk_fma_f32 v[74:75], v[74:75], v[80:81], v[76:77]
	v_mul_f32_e32 v76, 0xbfb8aa3b, v88
	v_mul_f32_e32 v77, 0xbfb8aa3b, v89
	v_exp_f32_e32 v76, v76
	v_exp_f32_e32 v77, v77
	v_lshlrev_b32_e32 v80, 16, v78
	v_and_b32_e32 v81, 0xffff0000, v78
	v_add_f32_e32 v76, 1.0, v76
	v_add_f32_e32 v77, 1.0, v77
	v_rcp_f32_e32 v76, v76
	v_rcp_f32_e32 v77, v77
	v_lshlrev_b32_e32 v78, 16, v79
	v_and_b32_e32 v79, 0xffff0000, v79
	v_pk_fma_f32 v[76:77], v[68:69], v[76:77], v[80:81]
	v_mul_f32_e32 v68, 0xbfb8aa3b, v90
	v_mul_f32_e32 v69, 0xbfb8aa3b, v91
	v_exp_f32_e32 v68, v68
	v_exp_f32_e32 v69, v69
	v_add_f32_e32 v68, 1.0, v68
	v_add_f32_e32 v69, 1.0, v69
	v_rcp_f32_e32 v68, v68
	v_rcp_f32_e32 v69, v69
	s_nop 0
	v_pk_fma_f32 v[78:79], v[70:71], v[68:69], v[78:79]
	v_cvt_pk_bf16_f32 v68, v72, v73
	v_cvt_pk_bf16_f32 v69, v74, v75
	v_cvt_pk_bf16_f32 v70, v76, v77
	v_cvt_pk_bf16_f32 v71, v78, v79
	global_store_dwordx4 v[86:87], v[68:71], off offset:256
	s_nop 1
	v_add_u32_e32 v235, 0x210000, v232
	v_add_u32_e32 v236, 0x252000, v232
	global_load_dwordx4 v[200:203], v235, s[8:9]
	global_load_dwordx4 v[204:207], v235, s[8:9] offset:256
	global_load_dwordx4 v[208:211], v236, s[8:9]
	global_load_dwordx4 v[212:215], v236, s[8:9] offset:256
	v_add_u32_e32 v235, 0x40000, v233
	v_add_u32_e32 v236, 0x48000, v233
	global_load_dwordx4 v[216:219], v235, s[6:7]
	global_load_dwordx4 v[220:223], v235, s[6:7] offset:256
	global_load_dwordx4 v[224:227], v236, s[6:7]
	global_load_dwordx4 v[228:231], v236, s[6:7] offset:256
	s_waitcnt vmcnt(0)
; __device__ __forceinline__ void unpack8(const u32x4 w, float (&f)[8]) { f[0] = bflo(w.x); f[1] = bfhi(w.x); f[2] = bflo(w.y); f[3] = bfhi(w.y); f[4] = bflo(w.z); f[5] = bfhi(w.z); f[6] = bflo(w.w); f[7] = bfhi(w.w); }
; __device__ __forceinline__ u32x4 pack8(const float (&f)[8]) { u32x4 w; w.x = pk2(f[0], f[1]); w.y = pk2(f[2], f[3]); w.z = pk2(f[4], f[5]); w.w = pk2(f[6], f[7]); return w; }
; __device__ __forceinline__ float sigmoidf_(float x) { return __builtin_amdgcn_rcpf(1.0f + __expf(-x)); }
;     __device__ __forceinline__ void operator()(const f32x4 (&acc)[2][2][4][2], const pg8::Unit& u, int wr, int wc, int fr, int fq) const {
;     ...
;                 const size_t row = (size_t)(row0 + ai * 128 + m * 16);
; #pragma unroll
;                 for (int bj = 0; bj < 2; ++bj) {
;                     float gt[8], mv[8], o[8];
;                     unpack8(*(const u32x4*)(Z + row * ZW + goff + col0 + bj * 128), gt);
;                     if (!first) unpack8(*(const u32x4*)(Mb + row * D + col0 + bj * 128), mv);
; #pragma unroll
;                     for (int n = 0; n < 2; ++n)
; #pragma unroll
;                         for (int j = 0; j < 4; ++j) o[4 * n + j] = (first ? 0.f : mv[4 * n + j]) + sigmoidf_(gt[4 * n + j]) * acc[ai][bj][m][n][j];
;                     *(u32x4*)(Mb + row * D + col0 + bj * 128) = pack8(o);
	v_add_u32_e32 v68, 0x80, v152
	v_ashrrev_i32_e32 v69, 31, v68
	v_lshlrev_b64 v[74:75], 11, v[68:69]
	v_mad_i64_i32 v[68:69], s[4:5], v68, s33, v[150:151]
	v_lshl_add_u64 v[70:71], v[68:69], 0, v[148:149]
	v_lshl_add_u64 v[68:69], v[70:71], 0, s[16:17]
	v_add_co_u32_e32 v70, vcc, s0, v70
	s_nop 1
	v_addc_co_u32_e32 v71, vcc, 0, v71, vcc
	s_nop 1
	v_mov_b64_e32 v[70:71], v[200:201]
	v_mov_b64_e32 v[72:73], v[202:203]
	v_lshlrev_b32_e32 v76, 16, v70
	v_and_b32_e32 v77, 0xffff0000, v70
	v_lshlrev_b32_e32 v80, 16, v71
	v_and_b32_e32 v81, 0xffff0000, v71
	v_lshl_add_u64 v[70:71], s[6:7], 0, v[74:75]
	v_lshl_add_u64 v[70:71], v[70:71], 0, v[148:149]
	v_lshlrev_b32_e32 v82, 16, v72
	v_and_b32_e32 v83, 0xffff0000, v72
	v_lshlrev_b32_e32 v84, 16, v73
	v_and_b32_e32 v85, 0xffff0000, v73
	s_nop 1
	v_mov_b64_e32 v[72:73], v[216:217]
	v_mov_b64_e32 v[74:75], v[218:219]
	v_mul_f32_e32 v76, 0xbfb8aa3b, v76
	v_mul_f32_e32 v77, 0xbfb8aa3b, v77
	v_exp_f32_e32 v76, v76
	v_exp_f32_e32 v77, v77
	v_add_f32_e32 v76, 1.0, v76
	v_add_f32_e32 v77, 1.0, v77
	v_rcp_f32_e32 v76, v76
	v_rcp_f32_e32 v77, v77
	v_lshlrev_b32_e32 v78, 16, v72
	v_and_b32_e32 v79, 0xffff0000, v72
	v_mul_f32_e32 v72, 0xbfb8aa3b, v80
	v_exp_f32_e32 v72, v72
	v_pk_fma_f32 v[64:65], v[64:65], v[76:77], v[78:79]
	v_add_f32_e32 v72, 1.0, v72
	v_rcp_f32_e32 v76, v72
	v_mul_f32_e32 v72, 0xbfb8aa3b, v81
	v_exp_f32_e32 v72, v72
	s_nop 0
	v_add_f32_e32 v72, 1.0, v72
	v_rcp_f32_e32 v77, v72
	v_lshlrev_b32_e32 v72, 16, v73
	v_and_b32_e32 v73, 0xffff0000, v73
	v_pk_fma_f32 v[66:67], v[66:67], v[76:77], v[72:73]
	v_mul_f32_e32 v72, 0xbfb8aa3b, v82
	v_mul_f32_e32 v73, 0xbfb8aa3b, v83
	v_exp_f32_e32 v72, v72
	v_exp_f32_e32 v73, v73
	v_lshlrev_b32_e32 v76, 16, v74
	v_and_b32_e32 v77, 0xffff0000, v74
	v_add_f32_e32 v72, 1.0, v72
	v_add_f32_e32 v73, 1.0, v73
	v_rcp_f32_e32 v72, v72
	v_rcp_f32_e32 v73, v73
	v_lshlrev_b32_e32 v74, 16, v75
	v_and_b32_e32 v75, 0xffff0000, v75
	v_pk_fma_f32 v[72:73], v[60:61], v[72:73], v[76:77]
	v_mul_f32_e32 v60, 0xbfb8aa3b, v84
	v_mul_f32_e32 v61, 0xbfb8aa3b, v85
	v_exp_f32_e32 v60, v60
	v_exp_f32_e32 v61, v61
	v_add_f32_e32 v60, 1.0, v60
	v_add_f32_e32 v61, 1.0, v61
	v_rcp_f32_e32 v60, v60
	v_rcp_f32_e32 v61, v61
	s_nop 0
	v_pk_fma_f32 v[74:75], v[62:63], v[60:61], v[74:75]
	v_cvt_pk_bf16_f32 v60, v64, v65
	v_cvt_pk_bf16_f32 v61, v66, v67
	v_cvt_pk_bf16_f32 v62, v72, v73
	v_cvt_pk_bf16_f32 v63, v74, v75
	global_store_dwordx4 v[70:71], v[60:63], off
	s_nop 1
	v_mov_b64_e32 v[60:61], v[204:205]
	v_mov_b64_e32 v[62:63], v[206:207]
	v_lshlrev_b32_e32 v64, 16, v60
	v_and_b32_e32 v65, 0xffff0000, v60
	v_lshlrev_b32_e32 v68, 16, v61
	v_and_b32_e32 v69, 0xffff0000, v61
	v_lshlrev_b32_e32 v72, 16, v62
	v_and_b32_e32 v73, 0xffff0000, v62
	v_lshlrev_b32_e32 v74, 16, v63
	v_and_b32_e32 v75, 0xffff0000, v63
	s_nop 1
	v_mov_b64_e32 v[60:61], v[220:221]
	v_mov_b64_e32 v[62:63], v[222:223]
	v_mul_f32_e32 v64, 0xbfb8aa3b, v64
	v_mul_f32_e32 v65, 0xbfb8aa3b, v65
	v_exp_f32_e32 v64, v64
	v_exp_f32_e32 v65, v65
	v_add_f32_e32 v64, 1.0, v64
	v_add_f32_e32 v65, 1.0, v65
	v_rcp_f32_e32 v64, v64
	v_rcp_f32_e32 v65, v65
	v_lshlrev_b32_e32 v66, 16, v60
	v_and_b32_e32 v67, 0xffff0000, v60
	v_mul_f32_e32 v60, 0xbfb8aa3b, v68
	v_exp_f32_e32 v60, v60
	v_pk_fma_f32 v[56:57], v[56:57], v[64:65], v[66:67]
	v_add_f32_e32 v60, 1.0, v60
	v_rcp_f32_e32 v64, v60
	v_mul_f32_e32 v60, 0xbfb8aa3b, v69
	v_exp_f32_e32 v60, v60
	s_nop 0
	v_add_f32_e32 v60, 1.0, v60
	v_rcp_f32_e32 v65, v60
	v_lshlrev_b32_e32 v60, 16, v61
	v_and_b32_e32 v61, 0xffff0000, v61
	v_pk_fma_f32 v[58:59], v[58:59], v[64:65], v[60:61]
	v_mul_f32_e32 v60, 0xbfb8aa3b, v72
	v_mul_f32_e32 v61, 0xbfb8aa3b, v73
	v_exp_f32_e32 v60, v60
	v_exp_f32_e32 v61, v61
	v_lshlrev_b32_e32 v64, 16, v62
	v_and_b32_e32 v65, 0xffff0000, v62
	v_add_f32_e32 v60, 1.0, v60
	v_add_f32_e32 v61, 1.0, v61
	v_rcp_f32_e32 v60, v60
	v_rcp_f32_e32 v61, v61
	v_lshlrev_b32_e32 v62, 16, v63
	v_and_b32_e32 v63, 0xffff0000, v63
	v_pk_fma_f32 v[60:61], v[52:53], v[60:61], v[64:65]
	v_mul_f32_e32 v52, 0xbfb8aa3b, v74
	v_mul_f32_e32 v53, 0xbfb8aa3b, v75
	v_exp_f32_e32 v52, v52
	v_exp_f32_e32 v53, v53
	v_add_f32_e32 v52, 1.0, v52
	v_add_f32_e32 v53, 1.0, v53
	v_rcp_f32_e32 v52, v52
	v_rcp_f32_e32 v53, v53
	s_nop 0
	v_pk_fma_f32 v[62:63], v[54:55], v[52:53], v[62:63]
	v_cvt_pk_bf16_f32 v52, v56, v57
	v_cvt_pk_bf16_f32 v53, v58, v59
	v_cvt_pk_bf16_f32 v54, v60, v61
	v_cvt_pk_bf16_f32 v55, v62, v63
	global_store_dwordx4 v[70:71], v[52:55], off offset:256
	s_nop 1
	v_add_u32_e32 v52, 0x90, v152
	v_ashrrev_i32_e32 v53, 31, v52
	v_lshlrev_b64 v[58:59], 11, v[52:53]
	v_mad_i64_i32 v[52:53], s[4:5], v52, s33, v[150:151]
	v_lshl_add_u64 v[54:55], v[52:53], 0, v[148:149]
	v_lshl_add_u64 v[52:53], v[54:55], 0, s[16:17]
	v_add_co_u32_e32 v54, vcc, s0, v54
	s_nop 1
	v_addc_co_u32_e32 v55, vcc, 0, v55, vcc
	s_nop 1
	v_mov_b64_e32 v[54:55], v[208:209]
	v_mov_b64_e32 v[56:57], v[210:211]
	v_lshlrev_b32_e32 v60, 16, v54
	v_and_b32_e32 v61, 0xffff0000, v54
	v_lshlrev_b32_e32 v64, 16, v55
	v_and_b32_e32 v65, 0xffff0000, v55
	v_lshl_add_u64 v[54:55], s[6:7], 0, v[58:59]
	v_lshl_add_u64 v[54:55], v[54:55], 0, v[148:149]
	v_lshlrev_b32_e32 v66, 16, v56
	v_and_b32_e32 v67, 0xffff0000, v56
	v_lshlrev_b32_e32 v68, 16, v57
	v_and_b32_e32 v69, 0xffff0000, v57
	s_nop 1
	v_mov_b64_e32 v[56:57], v[224:225]
	v_mov_b64_e32 v[58:59], v[226:227]
	v_mul_f32_e32 v60, 0xbfb8aa3b, v60
	v_mul_f32_e32 v61, 0xbfb8aa3b, v61
	v_exp_f32_e32 v60, v60
	v_exp_f32_e32 v61, v61
	v_add_f32_e32 v60, 1.0, v60
	v_add_f32_e32 v61, 1.0, v61
	v_rcp_f32_e32 v60, v60
	v_rcp_f32_e32 v61, v61
	v_lshlrev_b32_e32 v62, 16, v56
	v_and_b32_e32 v63, 0xffff0000, v56
; __device__ __forceinline__ void unpack8(const u32x4 w, float (&f)[8]) { f[0] = bflo(w.x); f[1] = bfhi(w.x); f[2] = bflo(w.y); f[3] = bfhi(w.y); f[4] = bflo(w.z); f[5] = bfhi(w.z); f[6] = bflo(w.w); f[7] = bfhi(w.w); }
; __device__ __forceinline__ u32x4 pack8(const float (&f)[8]) { u32x4 w; w.x = pk2(f[0], f[1]); w.y = pk2(f[2], f[3]); w.z = pk2(f[4], f[5]); w.w = pk2(f[6], f[7]); return w; }
; __device__ __forceinline__ float sigmoidf_(float x) { return __builtin_amdgcn_rcpf(1.0f + __expf(-x)); }
;     __device__ __forceinline__ void operator()(const f32x4 (&acc)[2][2][4][2], const pg8::Unit& u, int wr, int wc, int fr, int fq) const {
;     ...
;                 const size_t row = (size_t)(row0 + ai * 128 + m * 16);
; #pragma unroll
;                 for (int bj = 0; bj < 2; ++bj) {
;                     float gt[8], mv[8], o[8];
;                     unpack8(*(const u32x4*)(Z + row * ZW + goff + col0 + bj * 128), gt);
;                     if (!first) unpack8(*(const u32x4*)(Mb + row * D + col0 + bj * 128), mv);
; #pragma unroll
;                     for (int n = 0; n < 2; ++n)
; #pragma unroll
;                         for (int j = 0; j < 4; ++j) o[4 * n + j] = (first ? 0.f : mv[4 * n + j]) + sigmoidf_(gt[4 * n + j]) * acc[ai][bj][m][n][j];
;                     *(u32x4*)(Mb + row * D + col0 + bj * 128) = pack8(o);
	v_mul_f32_e32 v56, 0xbfb8aa3b, v64
	v_exp_f32_e32 v56, v56
	v_pk_fma_f32 v[48:49], v[48:49], v[60:61], v[62:63]
	v_add_f32_e32 v56, 1.0, v56
	v_rcp_f32_e32 v60, v56
	v_mul_f32_e32 v56, 0xbfb8aa3b, v65
	v_exp_f32_e32 v56, v56
	s_nop 0
	v_add_f32_e32 v56, 1.0, v56
	v_rcp_f32_e32 v61, v56
	v_lshlrev_b32_e32 v56, 16, v57
	v_and_b32_e32 v57, 0xffff0000, v57
	v_pk_fma_f32 v[50:51], v[50:51], v[60:61], v[56:57]
	v_mul_f32_e32 v56, 0xbfb8aa3b, v66
	v_mul_f32_e32 v57, 0xbfb8aa3b, v67
	v_exp_f32_e32 v56, v56
	v_exp_f32_e32 v57, v57
	v_lshlrev_b32_e32 v60, 16, v58
	v_and_b32_e32 v61, 0xffff0000, v58
	v_add_f32_e32 v56, 1.0, v56
	v_add_f32_e32 v57, 1.0, v57
	v_rcp_f32_e32 v56, v56
	v_rcp_f32_e32 v57, v57
	v_lshlrev_b32_e32 v58, 16, v59
	v_and_b32_e32 v59, 0xffff0000, v59
	v_pk_fma_f32 v[56:57], v[44:45], v[56:57], v[60:61]
	v_mul_f32_e32 v44, 0xbfb8aa3b, v68
	v_mul_f32_e32 v45, 0xbfb8aa3b, v69
	v_exp_f32_e32 v44, v44
	v_exp_f32_e32 v45, v45
	v_add_f32_e32 v44, 1.0, v44
	v_add_f32_e32 v45, 1.0, v45
	v_rcp_f32_e32 v44, v44
	v_rcp_f32_e32 v45, v45
	s_nop 0
	v_pk_fma_f32 v[58:59], v[46:47], v[44:45], v[58:59]
	v_cvt_pk_bf16_f32 v44, v48, v49
	v_cvt_pk_bf16_f32 v45, v50, v51
	v_cvt_pk_bf16_f32 v46, v56, v57
	v_cvt_pk_bf16_f32 v47, v58, v59
	global_store_dwordx4 v[54:55], v[44:47], off
	s_nop 1
	v_mov_b64_e32 v[44:45], v[212:213]
	v_mov_b64_e32 v[46:47], v[214:215]
	v_lshlrev_b32_e32 v48, 16, v44
	v_and_b32_e32 v49, 0xffff0000, v44
	v_lshlrev_b32_e32 v52, 16, v45
	v_and_b32_e32 v53, 0xffff0000, v45
	v_lshlrev_b32_e32 v56, 16, v46
	v_and_b32_e32 v57, 0xffff0000, v46
	v_lshlrev_b32_e32 v58, 16, v47
	v_and_b32_e32 v59, 0xffff0000, v47
	s_nop 1
	v_mov_b64_e32 v[44:45], v[228:229]
	v_mov_b64_e32 v[46:47], v[230:231]
	v_mul_f32_e32 v48, 0xbfb8aa3b, v48
	v_mul_f32_e32 v49, 0xbfb8aa3b, v49
	v_exp_f32_e32 v48, v48
	v_exp_f32_e32 v49, v49
	v_add_f32_e32 v48, 1.0, v48
	v_add_f32_e32 v49, 1.0, v49
	v_rcp_f32_e32 v48, v48
	v_rcp_f32_e32 v49, v49
	v_lshlrev_b32_e32 v50, 16, v44
	v_and_b32_e32 v51, 0xffff0000, v44
	v_mul_f32_e32 v44, 0xbfb8aa3b, v52
	v_exp_f32_e32 v44, v44
	v_pk_fma_f32 v[40:41], v[40:41], v[48:49], v[50:51]
	v_add_f32_e32 v44, 1.0, v44
	v_rcp_f32_e32 v48, v44
	v_mul_f32_e32 v44, 0xbfb8aa3b, v53
	v_exp_f32_e32 v44, v44
	s_nop 0
	v_add_f32_e32 v44, 1.0, v44
	v_rcp_f32_e32 v49, v44
	v_lshlrev_b32_e32 v44, 16, v45
	v_and_b32_e32 v45, 0xffff0000, v45
	v_pk_fma_f32 v[42:43], v[42:43], v[48:49], v[44:45]
	v_mul_f32_e32 v44, 0xbfb8aa3b, v56
	v_mul_f32_e32 v45, 0xbfb8aa3b, v57
	v_exp_f32_e32 v44, v44
	v_exp_f32_e32 v45, v45
	v_lshlrev_b32_e32 v48, 16, v46
	v_and_b32_e32 v49, 0xffff0000, v46
	v_add_f32_e32 v44, 1.0, v44
	v_add_f32_e32 v45, 1.0, v45
	v_rcp_f32_e32 v44, v44
	v_rcp_f32_e32 v45, v45
	v_lshlrev_b32_e32 v46, 16, v47
	v_and_b32_e32 v47, 0xffff0000, v47
	v_pk_fma_f32 v[44:45], v[36:37], v[44:45], v[48:49]
	v_mul_f32_e32 v36, 0xbfb8aa3b, v58
	v_mul_f32_e32 v37, 0xbfb8aa3b, v59
	v_exp_f32_e32 v36, v36
	v_exp_f32_e32 v37, v37
	v_add_f32_e32 v36, 1.0, v36
	v_add_f32_e32 v37, 1.0, v37
	v_rcp_f32_e32 v36, v36
	v_rcp_f32_e32 v37, v37
	s_nop 0
	v_pk_fma_f32 v[46:47], v[38:39], v[36:37], v[46:47]
	v_cvt_pk_bf16_f32 v36, v40, v41
	v_cvt_pk_bf16_f32 v37, v42, v43
	v_cvt_pk_bf16_f32 v38, v44, v45
	v_cvt_pk_bf16_f32 v39, v46, v47
	global_store_dwordx4 v[54:55], v[36:39], off offset:256
	s_nop 1
	v_add_u32_e32 v235, 0x294000, v232
	v_add_u32_e32 v236, 0x2d6000, v232
	global_load_dwordx4 v[200:203], v235, s[8:9]
	global_load_dwordx4 v[204:207], v235, s[8:9] offset:256
	global_load_dwordx4 v[208:211], v236, s[8:9]
	global_load_dwordx4 v[212:215], v236, s[8:9] offset:256
	v_add_u32_e32 v235, 0x50000, v233
	v_add_u32_e32 v236, 0x58000, v233
	global_load_dwordx4 v[216:219], v235, s[6:7]
	global_load_dwordx4 v[220:223], v235, s[6:7] offset:256
	global_load_dwordx4 v[224:227], v236, s[6:7]
	global_load_dwordx4 v[228:231], v236, s[6:7] offset:256
	s_waitcnt vmcnt(0)
	v_add_u32_e32 v36, 0xa0, v152
	v_ashrrev_i32_e32 v37, 31, v36
	v_lshlrev_b64 v[42:43], 11, v[36:37]
	v_mad_i64_i32 v[36:37], s[4:5], v36, s33, v[150:151]
	v_lshl_add_u64 v[38:39], v[36:37], 0, v[148:149]
	v_lshl_add_u64 v[36:37], v[38:39], 0, s[16:17]
	v_add_co_u32_e32 v38, vcc, s0, v38
	s_nop 1
	v_addc_co_u32_e32 v39, vcc, 0, v39, vcc
	s_nop 1
	v_mov_b64_e32 v[38:39], v[200:201]
	v_mov_b64_e32 v[40:41], v[202:203]
	v_lshlrev_b32_e32 v44, 16, v38
	v_and_b32_e32 v45, 0xffff0000, v38
	v_lshlrev_b32_e32 v48, 16, v39
	v_and_b32_e32 v49, 0xffff0000, v39
	v_lshl_add_u64 v[38:39], s[6:7], 0, v[42:43]
	v_lshl_add_u64 v[38:39], v[38:39], 0, v[148:149]
	v_lshlrev_b32_e32 v50, 16, v40
	v_and_b32_e32 v51, 0xffff0000, v40
	v_lshlrev_b32_e32 v52, 16, v41
	v_and_b32_e32 v53, 0xffff0000, v41
	s_nop 1
	v_mov_b64_e32 v[40:41], v[216:217]
	v_mov_b64_e32 v[42:43], v[218:219]
	v_mul_f32_e32 v44, 0xbfb8aa3b, v44
	v_mul_f32_e32 v45, 0xbfb8aa3b, v45
	v_exp_f32_e32 v44, v44
	v_exp_f32_e32 v45, v45
	v_add_f32_e32 v44, 1.0, v44
	v_add_f32_e32 v45, 1.0, v45
	v_rcp_f32_e32 v44, v44
	v_rcp_f32_e32 v45, v45
	v_lshlrev_b32_e32 v46, 16, v40
	v_and_b32_e32 v47, 0xffff0000, v40
	v_mul_f32_e32 v40, 0xbfb8aa3b, v48
	v_exp_f32_e32 v40, v40
	v_pk_fma_f32 v[32:33], v[32:33], v[44:45], v[46:47]
	v_add_f32_e32 v40, 1.0, v40
	v_rcp_f32_e32 v44, v40
	v_mul_f32_e32 v40, 0xbfb8aa3b, v49
	v_exp_f32_e32 v40, v40
	s_nop 0
	v_add_f32_e32 v40, 1.0, v40
	v_rcp_f32_e32 v45, v40
	v_lshlrev_b32_e32 v40, 16, v41
	v_and_b32_e32 v41, 0xffff0000, v41
	v_pk_fma_f32 v[34:35], v[34:35], v[44:45], v[40:41]
	v_mul_f32_e32 v40, 0xbfb8aa3b, v50
	v_mul_f32_e32 v41, 0xbfb8aa3b, v51
	v_exp_f32_e32 v40, v40
	v_exp_f32_e32 v41, v41
	v_lshlrev_b32_e32 v44, 16, v42
; __device__ __forceinline__ void unpack8(const u32x4 w, float (&f)[8]) { f[0] = bflo(w.x); f[1] = bfhi(w.x); f[2] = bflo(w.y); f[3] = bfhi(w.y); f[4] = bflo(w.z); f[5] = bfhi(w.z); f[6] = bflo(w.w); f[7] = bfhi(w.w); }
; __device__ __forceinline__ u32x4 pack8(const float (&f)[8]) { u32x4 w; w.x = pk2(f[0], f[1]); w.y = pk2(f[2], f[3]); w.z = pk2(f[4], f[5]); w.w = pk2(f[6], f[7]); return w; }
; __device__ __forceinline__ float sigmoidf_(float x) { return __builtin_amdgcn_rcpf(1.0f + __expf(-x)); }
;     __device__ __forceinline__ void operator()(const f32x4 (&acc)[2][2][4][2], const pg8::Unit& u, int wr, int wc, int fr, int fq) const {
;     ...
;                 const size_t row = (size_t)(row0 + ai * 128 + m * 16);
; #pragma unroll
;                 for (int bj = 0; bj < 2; ++bj) {
;                     float gt[8], mv[8], o[8];
;                     unpack8(*(const u32x4*)(Z + row * ZW + goff + col0 + bj * 128), gt);
;                     if (!first) unpack8(*(const u32x4*)(Mb + row * D + col0 + bj * 128), mv);
; #pragma unroll
;                     for (int n = 0; n < 2; ++n)
; #pragma unroll
;                         for (int j = 0; j < 4; ++j) o[4 * n + j] = (first ? 0.f : mv[4 * n + j]) + sigmoidf_(gt[4 * n + j]) * acc[ai][bj][m][n][j];
;                     *(u32x4*)(Mb + row * D + col0 + bj * 128) = pack8(o);
	v_and_b32_e32 v45, 0xffff0000, v42
	v_add_f32_e32 v40, 1.0, v40
	v_add_f32_e32 v41, 1.0, v41
	v_rcp_f32_e32 v40, v40
	v_rcp_f32_e32 v41, v41
	v_lshlrev_b32_e32 v42, 16, v43
	v_and_b32_e32 v43, 0xffff0000, v43
	v_pk_fma_f32 v[40:41], v[24:25], v[40:41], v[44:45]
	v_mul_f32_e32 v24, 0xbfb8aa3b, v52
	v_mul_f32_e32 v25, 0xbfb8aa3b, v53
	v_exp_f32_e32 v24, v24
	v_exp_f32_e32 v25, v25
	v_add_f32_e32 v24, 1.0, v24
	v_add_f32_e32 v25, 1.0, v25
	v_rcp_f32_e32 v24, v24
	v_rcp_f32_e32 v25, v25
	s_nop 0
	v_pk_fma_f32 v[42:43], v[26:27], v[24:25], v[42:43]
	v_cvt_pk_bf16_f32 v24, v32, v33
	v_cvt_pk_bf16_f32 v25, v34, v35
	v_cvt_pk_bf16_f32 v26, v40, v41
	v_cvt_pk_bf16_f32 v27, v42, v43
	global_store_dwordx4 v[38:39], v[24:27], off
	s_nop 1
	v_mov_b64_e32 v[24:25], v[204:205]
	v_mov_b64_e32 v[26:27], v[206:207]
	v_lshlrev_b32_e32 v32, 16, v24
	v_and_b32_e32 v33, 0xffff0000, v24
	v_lshlrev_b32_e32 v36, 16, v25
	v_and_b32_e32 v37, 0xffff0000, v25
	v_lshlrev_b32_e32 v40, 16, v26
	v_and_b32_e32 v41, 0xffff0000, v26
	v_lshlrev_b32_e32 v42, 16, v27
	v_and_b32_e32 v43, 0xffff0000, v27
	s_nop 1
	v_mov_b64_e32 v[24:25], v[220:221]
	v_mov_b64_e32 v[26:27], v[222:223]
	v_mul_f32_e32 v32, 0xbfb8aa3b, v32
	v_mul_f32_e32 v33, 0xbfb8aa3b, v33
	v_exp_f32_e32 v32, v32
	v_exp_f32_e32 v33, v33
	v_add_f32_e32 v32, 1.0, v32
	v_add_f32_e32 v33, 1.0, v33
	v_rcp_f32_e32 v32, v32
	v_rcp_f32_e32 v33, v33
	v_lshlrev_b32_e32 v34, 16, v24
	v_and_b32_e32 v35, 0xffff0000, v24
	v_mul_f32_e32 v24, 0xbfb8aa3b, v36
	v_exp_f32_e32 v24, v24
	v_pk_fma_f32 v[20:21], v[20:21], v[32:33], v[34:35]
	v_add_f32_e32 v24, 1.0, v24
	v_rcp_f32_e32 v32, v24
	v_mul_f32_e32 v24, 0xbfb8aa3b, v37
	v_exp_f32_e32 v24, v24
	s_nop 0
	v_add_f32_e32 v24, 1.0, v24
	v_rcp_f32_e32 v33, v24
	v_lshlrev_b32_e32 v24, 16, v25
	v_and_b32_e32 v25, 0xffff0000, v25
	v_pk_fma_f32 v[22:23], v[22:23], v[32:33], v[24:25]
	v_mul_f32_e32 v24, 0xbfb8aa3b, v40
	v_mul_f32_e32 v25, 0xbfb8aa3b, v41
	v_exp_f32_e32 v24, v24
	v_exp_f32_e32 v25, v25
	v_lshlrev_b32_e32 v32, 16, v26
	v_and_b32_e32 v33, 0xffff0000, v26
	v_add_f32_e32 v24, 1.0, v24
	v_add_f32_e32 v25, 1.0, v25
	v_rcp_f32_e32 v24, v24
	v_rcp_f32_e32 v25, v25
	v_lshlrev_b32_e32 v26, 16, v27
	v_and_b32_e32 v27, 0xffff0000, v27
	v_pk_fma_f32 v[24:25], v[16:17], v[24:25], v[32:33]
	v_mul_f32_e32 v16, 0xbfb8aa3b, v42
	v_mul_f32_e32 v17, 0xbfb8aa3b, v43
	v_exp_f32_e32 v16, v16
	v_exp_f32_e32 v17, v17
	v_add_f32_e32 v16, 1.0, v16
	v_add_f32_e32 v17, 1.0, v17
	v_rcp_f32_e32 v16, v16
	v_rcp_f32_e32 v17, v17
	s_nop 0
	v_pk_fma_f32 v[26:27], v[18:19], v[16:17], v[26:27]
	v_cvt_pk_bf16_f32 v16, v20, v21
	v_cvt_pk_bf16_f32 v17, v22, v23
	v_cvt_pk_bf16_f32 v18, v24, v25
	v_cvt_pk_bf16_f32 v19, v26, v27
	global_store_dwordx4 v[38:39], v[16:19], off offset:256
	s_nop 1
	v_add_u32_e32 v16, 0xb0, v152
	v_ashrrev_i32_e32 v17, 31, v16
	v_lshlrev_b64 v[24:25], 11, v[16:17]
	v_mad_i64_i32 v[16:17], s[4:5], v16, s33, v[150:151]
	v_lshl_add_u64 v[16:17], v[16:17], 0, v[148:149]
	v_lshl_add_u64 v[18:19], v[16:17], 0, s[16:17]
	v_add_co_u32_e32 v16, vcc, s0, v16
	s_mov_b32 s0, s54
	s_nop 0
	v_addc_co_u32_e32 v17, vcc, 0, v17, vcc
	s_nop 1
	v_mov_b64_e32 v[20:21], v[208:209]
	v_mov_b64_e32 v[22:23], v[210:211]
	v_lshl_add_u64 v[16:17], s[6:7], 0, v[24:25]
	v_lshl_add_u64 v[16:17], v[16:17], 0, v[148:149]
	s_and_b64 vcc, exec, s[2:3]
	s_mov_b64 s[16:17], s[12:13]
	v_lshlrev_b32_e32 v26, 16, v20
	v_and_b32_e32 v27, 0xffff0000, v20
	v_lshlrev_b32_e32 v32, 16, v21
	v_and_b32_e32 v33, 0xffff0000, v21
	v_lshlrev_b32_e32 v34, 16, v22
	v_and_b32_e32 v35, 0xffff0000, v22
	v_lshlrev_b32_e32 v36, 16, v23
	v_and_b32_e32 v37, 0xffff0000, v23
	s_nop 1
	v_mov_b64_e32 v[20:21], v[224:225]
; __device__ __forceinline__ void unpack8(const u32x4 w, float (&f)[8]) { f[0] = bflo(w.x); f[1] = bfhi(w.x); f[2] = bflo(w.y); f[3] = bfhi(w.y); f[4] = bflo(w.z); f[5] = bfhi(w.z); f[6] = bflo(w.w); f[7] = bfhi(w.w); }
; __device__ __forceinline__ u32x4 pack8(const float (&f)[8]) { u32x4 w; w.x = pk2(f[0], f[1]); w.y = pk2(f[2], f[3]); w.z = pk2(f[4], f[5]); w.w = pk2(f[6], f[7]); return w; }
; __device__ __forceinline__ float sigmoidf_(float x) { return __builtin_amdgcn_rcpf(1.0f + __expf(-x)); }
;     __device__ __forceinline__ void operator()(const f32x4 (&acc)[2][2][4][2], const pg8::Unit& u, int wr, int wc, int fr, int fq) const {
;     ...
;                 const size_t row = (size_t)(row0 + ai * 128 + m * 16);
; #pragma unroll
;                 for (int bj = 0; bj < 2; ++bj) {
;                     float gt[8], mv[8], o[8];
;                     unpack8(*(const u32x4*)(Z + row * ZW + goff + col0 + bj * 128), gt);
;                     if (!first) unpack8(*(const u32x4*)(Mb + row * D + col0 + bj * 128), mv);
; #pragma unroll
;                     for (int n = 0; n < 2; ++n)
; #pragma unroll
;                         for (int j = 0; j < 4; ++j) o[4 * n + j] = (first ? 0.f : mv[4 * n + j]) + sigmoidf_(gt[4 * n + j]) * acc[ai][bj][m][n][j];
;                     *(u32x4*)(Mb + row * D + col0 + bj * 128) = pack8(o);
	v_mov_b64_e32 v[22:23], v[226:227]
	v_mul_f32_e32 v24, 0xbfb8aa3b, v26
	v_mul_f32_e32 v25, 0xbfb8aa3b, v27
	v_exp_f32_e32 v24, v24
	v_exp_f32_e32 v25, v25
	v_add_f32_e32 v24, 1.0, v24
	v_add_f32_e32 v25, 1.0, v25
	v_rcp_f32_e32 v24, v24
	v_rcp_f32_e32 v25, v25
	v_lshlrev_b32_e32 v26, 16, v20
	v_and_b32_e32 v27, 0xffff0000, v20
	v_mul_f32_e32 v20, 0xbfb8aa3b, v32
	v_exp_f32_e32 v20, v20
	v_pk_fma_f32 v[12:13], v[12:13], v[24:25], v[26:27]
	v_add_f32_e32 v20, 1.0, v20
	v_rcp_f32_e32 v24, v20
	v_mul_f32_e32 v20, 0xbfb8aa3b, v33
	v_exp_f32_e32 v20, v20
	s_nop 0
	v_add_f32_e32 v20, 1.0, v20
	v_rcp_f32_e32 v25, v20
	v_lshlrev_b32_e32 v20, 16, v21
	v_and_b32_e32 v21, 0xffff0000, v21
	v_pk_fma_f32 v[14:15], v[14:15], v[24:25], v[20:21]
	v_mul_f32_e32 v20, 0xbfb8aa3b, v34
	v_mul_f32_e32 v21, 0xbfb8aa3b, v35
	v_exp_f32_e32 v20, v20
	v_exp_f32_e32 v21, v21
	v_lshlrev_b32_e32 v24, 16, v22
	v_and_b32_e32 v25, 0xffff0000, v22
	v_add_f32_e32 v20, 1.0, v20
	v_add_f32_e32 v21, 1.0, v21
	v_rcp_f32_e32 v20, v20
	v_rcp_f32_e32 v21, v21
	v_lshlrev_b32_e32 v22, 16, v23
	v_and_b32_e32 v23, 0xffff0000, v23
	v_pk_fma_f32 v[20:21], v[8:9], v[20:21], v[24:25]
	v_mul_f32_e32 v8, 0xbfb8aa3b, v36
	v_mul_f32_e32 v9, 0xbfb8aa3b, v37
	v_exp_f32_e32 v8, v8
	v_exp_f32_e32 v9, v9
	v_add_f32_e32 v8, 1.0, v8
	v_add_f32_e32 v9, 1.0, v9
	v_rcp_f32_e32 v8, v8
	v_rcp_f32_e32 v9, v9
	s_nop 0
	v_pk_fma_f32 v[22:23], v[10:11], v[8:9], v[22:23]
	v_cvt_pk_bf16_f32 v8, v12, v13
	v_cvt_pk_bf16_f32 v9, v14, v15
	v_cvt_pk_bf16_f32 v10, v20, v21
	v_cvt_pk_bf16_f32 v11, v22, v23
	global_store_dwordx4 v[16:17], v[8:11], off
	s_nop 1
	v_mov_b64_e32 v[12:13], v[212:213]
	v_mov_b64_e32 v[14:15], v[214:215]
	s_nop 0
	s_nop 1
	v_mov_b64_e32 v[8:9], v[228:229]
	v_mov_b64_e32 v[10:11], v[230:231]
	v_lshlrev_b32_e32 v18, 16, v12
	v_and_b32_e32 v19, 0xffff0000, v12
	v_lshlrev_b32_e32 v20, 16, v13
	v_and_b32_e32 v21, 0xffff0000, v13
	v_mul_f32_e32 v12, 0xbfb8aa3b, v18
	v_mul_f32_e32 v13, 0xbfb8aa3b, v19
	v_exp_f32_e32 v12, v12
	v_exp_f32_e32 v13, v13
	v_lshlrev_b32_e32 v22, 16, v14
	v_and_b32_e32 v23, 0xffff0000, v14
	v_lshlrev_b32_e32 v24, 16, v15
	v_and_b32_e32 v25, 0xffff0000, v15
	v_lshlrev_b32_e32 v14, 16, v8
	v_and_b32_e32 v15, 0xffff0000, v8
	v_mul_f32_e32 v8, 0xbfb8aa3b, v20
	v_add_f32_e32 v12, 1.0, v12
	v_add_f32_e32 v13, 1.0, v13
	v_exp_f32_e32 v8, v8
	v_rcp_f32_e32 v12, v12
	v_rcp_f32_e32 v13, v13
	v_add_f32_e32 v8, 1.0, v8
	v_pk_fma_f32 v[4:5], v[4:5], v[12:13], v[14:15]
	v_rcp_f32_e32 v12, v8
	v_mul_f32_e32 v8, 0xbfb8aa3b, v21
	v_exp_f32_e32 v8, v8
	s_nop 0
	v_add_f32_e32 v8, 1.0, v8
	v_rcp_f32_e32 v13, v8
	v_lshlrev_b32_e32 v8, 16, v9
	v_and_b32_e32 v9, 0xffff0000, v9
	v_pk_fma_f32 v[6:7], v[6:7], v[12:13], v[8:9]
	v_mul_f32_e32 v8, 0xbfb8aa3b, v22
	v_mul_f32_e32 v9, 0xbfb8aa3b, v23
	v_exp_f32_e32 v8, v8
	v_exp_f32_e32 v9, v9
	v_lshlrev_b32_e32 v12, 16, v10
	v_and_b32_e32 v13, 0xffff0000, v10
	v_add_f32_e32 v8, 1.0, v8
	v_add_f32_e32 v9, 1.0, v9
	v_rcp_f32_e32 v8, v8
	v_rcp_f32_e32 v9, v9
	v_lshlrev_b32_e32 v10, 16, v11
	v_and_b32_e32 v11, 0xffff0000, v11
	v_pk_fma_f32 v[8:9], v[0:1], v[8:9], v[12:13]
	v_mul_f32_e32 v0, 0xbfb8aa3b, v24
	v_mul_f32_e32 v1, 0xbfb8aa3b, v25
	v_exp_f32_e32 v0, v0
	v_exp_f32_e32 v1, v1
	v_add_f32_e32 v0, 1.0, v0
	v_add_f32_e32 v1, 1.0, v1
	v_rcp_f32_e32 v0, v0
	v_rcp_f32_e32 v1, v1
	s_nop 0
	v_pk_fma_f32 v[10:11], v[2:3], v[0:1], v[10:11]
	v_cvt_pk_bf16_f32 v0, v4, v5
	v_cvt_pk_bf16_f32 v1, v6, v7
	v_cvt_pk_bf16_f32 v2, v8, v9
	v_cvt_pk_bf16_f32 v3, v10, v11
	global_store_dwordx4 v[16:17], v[0:3], off offset:256
	s_cbranch_vccz .LBB0_1854
	s_waitcnt vmcnt(0)
	s_cmpk_gt_u32 s23, 0xff
	s_cbranch_scc1 .LBB0_1867
	s_barrier
